# BAR steps: two v_exp groups (16) before the first QK MFMA
# baseline (speedup 1.0000x reference)
.LBB0_641:
	s_add_i32 s24, s23, -7
	s_lshl_b32 s92, s24, 13
	s_add_u32 vcc_lo, s100, s92
	s_addc_u32 vcc_hi, s101, 0
	global_load_dwordx4 v[52:55], v248, vcc
	s_add_i32 s24, s23, -8
	s_lshl_b32 s92, s24, 7
	s_add_u32 vcc_lo, s98, s92
	s_addc_u32 vcc_hi, s99, 0
	global_load_dwordx4 v[56:59], v249, vcc
	s_mul_i32 s26, s25, 0x2400
	s_add_i32 s24, s23, -7
	s_add_i32 s27, s26, 0xffffdc00
	s_cmp_lg_u32 s25, 0
	s_cselect_b32 s27, s27, 0x9000
	v_add_u32_e32 v1, s27, v163
	ds_read_b128 v[60:63], v1 offset:36864
	ds_read_b128 v[114:117], v1 offset:36896
	ds_read_b128 v[118:121], v1 offset:41472
	ds_read_b128 v[134:137], v1 offset:41504
	ds_read_b128 v[146:149], v1 offset:36928
	ds_read_b128 v[150:153], v1 offset:36960
	ds_read_b128 v[196:199], v1 offset:41536
	ds_read_b128 v[200:203], v1 offset:41568
	s_setprio 3
	v_cvt_pk_bf16_f32 v204, v102, v103
	v_cvt_pk_bf16_f32 v205, v104, v105
	v_cvt_pk_bf16_f32 v206, v98, v99
	v_cvt_pk_bf16_f32 v207, v100, v101
	s_waitcnt lgkmcnt(7)
	s_nop 0
	v_mfma_f32_32x32x16_bf16 v[18:33], v[60:63], v[204:207], v[18:33]
	v_add_f32_e32 v1, v102, v103
	v_add_f32_e32 v1, v1, v104
	v_add_f32_e32 v1, v1, v105
	s_waitcnt lgkmcnt(5)
	v_mfma_f32_32x32x16_bf16 v[2:17], v[118:121], v[204:207], v[2:17]
	v_cvt_pk_bf16_f32 v60, v194, v187
	v_cvt_pk_bf16_f32 v61, v186, v185
	v_cvt_pk_bf16_f32 v62, v133, v132
	v_cvt_pk_bf16_f32 v63, v131, v130
	v_add_f32_e32 v1, v1, v98
	v_add_f32_e32 v1, v1, v99
	v_add_f32_e32 v1, v1, v100
	v_add_f32_e32 v1, v1, v101
	s_nop 0
	v_mfma_f32_32x32x16_bf16 v[18:33], v[114:117], v[60:63], v[18:33]
	v_add_f32_e32 v1, v1, v194
	v_add_f32_e32 v1, v1, v187
	v_add_f32_e32 v1, v1, v186
	v_add_f32_e32 v1, v1, v185
	s_waitcnt lgkmcnt(4)
	v_mfma_f32_32x32x16_bf16 v[2:17], v[134:137], v[60:63], v[2:17]
	v_cvt_pk_bf16_f32 v98, v129, v128
	v_cvt_pk_bf16_f32 v99, v127, v126
	v_cvt_pk_bf16_f32 v100, v125, v124
	v_cvt_pk_bf16_f32 v101, v123, v122
	v_add_f32_e32 v1, v1, v133
	v_add_f32_e32 v1, v1, v132
	v_add_f32_e32 v1, v1, v131
	v_add_f32_e32 v1, v1, v130
	s_waitcnt lgkmcnt(3)
	v_mfma_f32_32x32x16_bf16 v[18:33], v[146:149], v[98:101], v[18:33]
	v_add_f32_e32 v1, v1, v129
	v_add_f32_e32 v1, v1, v128
	v_add_f32_e32 v1, v1, v127
	v_add_f32_e32 v1, v1, v126
	s_waitcnt lgkmcnt(1)
	v_mfma_f32_32x32x16_bf16 v[2:17], v[196:199], v[98:101], v[2:17]
	v_cvt_pk_bf16_f32 v60, v109, v108
	v_cvt_pk_bf16_f32 v61, v107, v106
	v_cvt_pk_bf16_f32 v62, v113, v112
	v_cvt_pk_bf16_f32 v63, v111, v110
	v_add_f32_e32 v1, v1, v125
	v_add_f32_e32 v1, v1, v124
	v_add_f32_e32 v1, v1, v123
	v_add_f32_e32 v1, v1, v122
	s_nop 0
	v_mfma_f32_32x32x16_bf16 v[18:33], v[150:153], v[60:63], v[18:33]
	v_add_f32_e32 v1, v1, v109
	v_add_f32_e32 v1, v1, v108
	v_add_f32_e32 v1, v1, v107
	v_add_f32_e32 v1, v1, v106
	s_waitcnt lgkmcnt(0)
	v_mfma_f32_32x32x16_bf16 v[2:17], v[200:203], v[60:63], v[2:17]
	v_add_f32_e32 v1, v1, v113
	v_add_f32_e32 v1, v1, v112
	v_add_f32_e32 v1, v1, v111
	v_add_f32_e32 v1, v1, v110
	s_setprio 2
	s_waitcnt lgkmcnt(0)
	s_barrier
	ds_read_b128 v[240:243], v165 offset:18432
	ds_read_b128 v[244:247], v165 offset:23040
	ds_read_b128 v[130:133], v165 offset:18464
	ds_read_b128 v[146:149], v165 offset:23072
	v_exp_f32_e32 v185, v82
	v_exp_f32_e32 v186, v83
	v_exp_f32_e32 v187, v84
	v_exp_f32_e32 v194, v85
	v_exp_f32_e32 v195, v86
	v_exp_f32_e32 v196, v87
	v_exp_f32_e32 v197, v88
	v_exp_f32_e32 v198, v89
	v_exp_f32_e32 v199, v90
	v_exp_f32_e32 v200, v91
	v_exp_f32_e32 v201, v92
	v_exp_f32_e32 v202, v93
	v_exp_f32_e32 v134, v94
	v_exp_f32_e32 v135, v95
	v_exp_f32_e32 v136, v96
	v_exp_f32_e32 v137, v97
	s_waitcnt lgkmcnt(2)
	v_mfma_f32_32x32x16_bf16 v[114:129], v[240:243], v[158:161], v[34:49]
	s_waitcnt lgkmcnt(1)
	v_mfma_f32_32x32x16_bf16 v[98:113], v[244:247], v[158:161], v[34:49]
	v_mfma_f32_32x32x16_bf16 v[114:129], v[130:133], v[154:157], v[114:129]
	v_exp_f32_e32 v96, v66
	v_exp_f32_e32 v97, v67
	v_exp_f32_e32 v203, v68
	v_exp_f32_e32 v204, v69
	v_exp_f32_e32 v130, v70
	v_exp_f32_e32 v131, v71
	v_exp_f32_e32 v132, v72
	v_exp_f32_e32 v133, v73
	s_waitcnt lgkmcnt(0)
	v_mfma_f32_32x32x16_bf16 v[98:113], v[146:149], v[154:157], v[98:113]
	v_exp_f32_e32 v205, v74
	v_exp_f32_e32 v206, v75
	v_exp_f32_e32 v207, v76
	v_exp_f32_e32 v208, v77
	v_exp_f32_e32 v209, v78
	v_exp_f32_e32 v210, v79
	v_exp_f32_e32 v211, v80
	v_exp_f32_e32 v212, v81
	v_add_u32_e32 v88, s26, v163
	ds_read_b128 v[240:243], v165 offset:27648
	ds_read_b128 v[244:247], v165 offset:32256
	ds_read_b128 v[60:63], v88 offset:41472
	ds_read_b128 v[64:67], v88 offset:36864
	ds_read_b128 v[68:71], v88 offset:36896
	ds_read_b128 v[72:75], v88 offset:41504
	ds_read_b128 v[76:79], v88 offset:36928
	ds_read_b128 v[80:83], v88 offset:41536
	ds_read_b128 v[84:87], v88 offset:36960
	ds_read_b128 v[88:91], v88 offset:41568
	s_cmp_gt_i32 s25, 2
	s_cselect_b32 s27, -3, 2
	s_add_i32 s27, s27, s25
	s_add_i32 s26, s23, -6
	s_mulk_i32 s27, 0x2400
	s_min_u32 s26, s26, s13
	v_add_u32_e32 v51, s27, v182
	s_min_u32 s24, s24, s13
	s_lshl_b32 s92, s26, 13
	s_waitcnt vmcnt(3)
	ds_write_b128 v182, v[138:141]
	s_waitcnt vmcnt(2)
	ds_write_b128 v51, v[142:145] offset:36864
	v_add_f32_e32 v1, v50, v1
	s_add_u32 vcc_lo, s100, s92
	s_addc_u32 vcc_hi, s101, 0
	global_load_dwordx4 v[146:149], v248, vcc
	s_lshl_b32 s92, s24, 7
	s_add_u32 vcc_lo, s98, s92
	s_addc_u32 vcc_hi, s99, 0
	global_load_dwordx4 v[150:153], v249, vcc
	s_add_i32 s27, s25, 1
	s_setprio 1
	v_cvt_pk_bf16_f32 v92, v185, v186
	v_cvt_pk_bf16_f32 v93, v187, v194
	v_cvt_pk_bf16_f32 v94, v195, v196
	v_cvt_pk_bf16_f32 v95, v197, v198
	s_waitcnt lgkmcnt(8)
	s_nop 0
	v_mfma_f32_32x32x16_bf16 v[18:33], v[64:67], v[92:95], v[18:33]
	v_add_f32_e32 v213, v185, v186
	v_add_f32_e32 v213, v213, v187
	v_add_f32_e32 v213, v213, v194
	s_nop 0
	v_mfma_f32_32x32x16_bf16 v[2:17], v[60:63], v[92:95], v[2:17]
	v_cvt_pk_bf16_f32 v64, v199, v200
	v_cvt_pk_bf16_f32 v65, v201, v202
	v_cvt_pk_bf16_f32 v66, v134, v135
	v_cvt_pk_bf16_f32 v67, v136, v137
	v_add_f32_e32 v213, v213, v195
	v_add_f32_e32 v213, v213, v196
	v_add_f32_e32 v213, v213, v197
	v_add_f32_e32 v213, v213, v198
	s_waitcnt lgkmcnt(7)
	v_mfma_f32_32x32x16_bf16 v[18:33], v[68:71], v[64:67], v[18:33]
	v_add_f32_e32 v213, v213, v199
	v_add_f32_e32 v213, v213, v200
	v_add_f32_e32 v213, v213, v201
	v_add_f32_e32 v213, v213, v202
	s_waitcnt lgkmcnt(6)
	v_mfma_f32_32x32x16_bf16 v[2:17], v[72:75], v[64:67], v[2:17]
	v_cvt_pk_bf16_f32 v60, v96, v97
	v_cvt_pk_bf16_f32 v61, v203, v204
	v_cvt_pk_bf16_f32 v62, v130, v131
	v_cvt_pk_bf16_f32 v63, v132, v133
	v_add_f32_e32 v213, v213, v134
	v_add_f32_e32 v213, v213, v135
	v_add_f32_e32 v213, v213, v136
	v_add_f32_e32 v213, v213, v137
	s_waitcnt lgkmcnt(5)
	v_mfma_f32_32x32x16_bf16 v[18:33], v[76:79], v[60:63], v[18:33]
	v_add_f32_e32 v213, v213, v96
	v_add_f32_e32 v213, v213, v97
	v_add_f32_e32 v213, v213, v203
	v_add_f32_e32 v213, v213, v204
	s_waitcnt lgkmcnt(4)
	v_mfma_f32_32x32x16_bf16 v[2:17], v[80:83], v[60:63], v[2:17]
	v_cvt_pk_bf16_f32 v64, v205, v206
	v_cvt_pk_bf16_f32 v65, v207, v208
	v_cvt_pk_bf16_f32 v66, v209, v210
	v_cvt_pk_bf16_f32 v67, v211, v212
	v_add_f32_e32 v213, v213, v130
	v_add_f32_e32 v213, v213, v131
	v_add_f32_e32 v213, v213, v132
	v_add_f32_e32 v213, v213, v133
	s_waitcnt lgkmcnt(3)
	v_mfma_f32_32x32x16_bf16 v[18:33], v[84:87], v[64:67], v[18:33]
	v_add_f32_e32 v213, v213, v205
	v_add_f32_e32 v213, v213, v206
	v_add_f32_e32 v213, v213, v207
	v_add_f32_e32 v213, v213, v208
	s_waitcnt lgkmcnt(2)
	v_mfma_f32_32x32x16_bf16 v[2:17], v[88:91], v[64:67], v[2:17]
	v_add_f32_e32 v213, v213, v209
	v_add_f32_e32 v213, v213, v210
	v_add_f32_e32 v213, v213, v211
	v_add_f32_e32 v213, v213, v212
	s_setprio 0
	ds_read_b128 v[64:67], v165 offset:27680
	ds_read_b128 v[72:75], v165 offset:32288
	s_cmp_lg_u32 s25, 4
	s_cselect_b32 s24, s27, 0
	s_waitcnt lgkmcnt(2)
	v_mfma_f32_32x32x16_bf16 v[130:145], v[240:243], v[158:161], v[34:49]
	v_exp_f32_e32 v185, v114
	v_exp_f32_e32 v186, v115
	v_exp_f32_e32 v187, v116
	v_exp_f32_e32 v194, v117
	v_exp_f32_e32 v195, v118
	v_exp_f32_e32 v196, v119
	v_exp_f32_e32 v197, v120
	v_exp_f32_e32 v198, v121
	s_waitcnt lgkmcnt(1)
	v_mfma_f32_32x32x16_bf16 v[82:97], v[244:247], v[158:161], v[34:49]
	v_exp_f32_e32 v199, v122
	v_exp_f32_e32 v200, v123
	v_exp_f32_e32 v201, v124
	v_exp_f32_e32 v202, v125
	v_exp_f32_e32 v122, v126
	v_exp_f32_e32 v123, v127
	v_exp_f32_e32 v124, v128
	v_exp_f32_e32 v125, v129
	v_mfma_f32_32x32x16_bf16 v[130:145], v[64:67], v[154:157], v[130:145]
	v_exp_f32_e32 v126, v98
	v_exp_f32_e32 v127, v99
	v_exp_f32_e32 v128, v100
	v_exp_f32_e32 v129, v101
	v_exp_f32_e32 v203, v102
	v_exp_f32_e32 v204, v103
	v_exp_f32_e32 v205, v104
	v_exp_f32_e32 v206, v105
	s_waitcnt lgkmcnt(0)
	v_mfma_f32_32x32x16_bf16 v[82:97], v[72:75], v[154:157], v[82:97]
	v_exp_f32_e32 v102, v106
	v_exp_f32_e32 v103, v107
	v_exp_f32_e32 v104, v108
	v_exp_f32_e32 v105, v109
	v_exp_f32_e32 v106, v110
	v_exp_f32_e32 v107, v111
	v_exp_f32_e32 v108, v112
	v_exp_f32_e32 v109, v113
	s_cmp_gt_i32 s24, 2
	s_cselect_b32 s25, -3, 2
	s_add_i32 s25, s25, s24
	s_mulk_i32 s25, 0x2400
	v_add_u32_e32 v50, s25, v182
	s_add_i32 s25, s24, 1
	s_cmp_lg_u32 s24, 4
	s_cselect_b32 s24, s25, 0
	s_add_i32 s25, s23, -5
	s_min_u32 s25, s25, s13
	s_lshl_b32 s92, s25, 13
	s_waitcnt vmcnt(3)
	ds_write_b128 v182, v[52:55] offset:9216
	s_waitcnt vmcnt(2)
	ds_write_b128 v50, v[56:59] offset:36864
	s_add_u32 vcc_lo, s100, s92
	s_addc_u32 vcc_hi, s101, 0
	global_load_dwordx4 v[118:121], v248, vcc
	s_lshl_b32 s92, s26, 7
	s_add_u32 vcc_lo, s98, s92
	s_addc_u32 vcc_hi, s99, 0
	global_load_dwordx4 v[114:117], v249, vcc
	s_mul_i32 s26, s24, 0x2400
	s_add_i32 s27, s26, 0xffffdc00
	s_cmp_lg_u32 s24, 0
	s_cselect_b32 s27, s27, 0x9000
	v_add_u32_e32 v78, s27, v163
	ds_read_b128 v[50:53], v78 offset:36864
	ds_read_b128 v[54:57], v78 offset:36896
	ds_read_b128 v[58:61], v78 offset:41472
	ds_read_b128 v[62:65], v78 offset:41504
	ds_read_b128 v[66:69], v78 offset:36928
	ds_read_b128 v[70:73], v78 offset:36960
	ds_read_b128 v[74:77], v78 offset:41536
	ds_read_b128 v[78:81], v78 offset:41568
	s_setprio 3
	v_cvt_pk_bf16_f32 v98, v185, v186
	v_cvt_pk_bf16_f32 v99, v187, v194
	v_cvt_pk_bf16_f32 v100, v195, v196
	v_cvt_pk_bf16_f32 v101, v197, v198
	s_waitcnt lgkmcnt(7)
	s_nop 0
	v_mfma_f32_32x32x16_bf16 v[18:33], v[50:53], v[98:101], v[18:33]
	v_add_f32_e32 v110, v185, v186
	v_add_f32_e32 v110, v110, v187
	v_add_f32_e32 v110, v110, v194
	s_waitcnt lgkmcnt(5)
	v_mfma_f32_32x32x16_bf16 v[2:17], v[58:61], v[98:101], v[2:17]
	v_cvt_pk_bf16_f32 v50, v199, v200
	v_cvt_pk_bf16_f32 v51, v201, v202
	v_cvt_pk_bf16_f32 v52, v122, v123
	v_cvt_pk_bf16_f32 v53, v124, v125
	v_add_f32_e32 v110, v110, v195
	v_add_f32_e32 v110, v110, v196
	v_add_f32_e32 v110, v110, v197
	v_add_f32_e32 v110, v110, v198
	s_nop 0
	v_mfma_f32_32x32x16_bf16 v[18:33], v[54:57], v[50:53], v[18:33]
	v_add_f32_e32 v110, v110, v199
	v_add_f32_e32 v110, v110, v200
	v_add_f32_e32 v110, v110, v201
	v_add_f32_e32 v110, v110, v202
	s_waitcnt lgkmcnt(4)
	v_mfma_f32_32x32x16_bf16 v[2:17], v[62:65], v[50:53], v[2:17]
	v_cvt_pk_bf16_f32 v54, v126, v127
	v_cvt_pk_bf16_f32 v55, v128, v129
	v_cvt_pk_bf16_f32 v56, v203, v204
	v_cvt_pk_bf16_f32 v57, v205, v206
	v_add_f32_e32 v110, v110, v122
	v_add_f32_e32 v110, v110, v123
	v_add_f32_e32 v110, v110, v124
	v_add_f32_e32 v110, v110, v125
	s_waitcnt lgkmcnt(3)
	v_mfma_f32_32x32x16_bf16 v[18:33], v[66:69], v[54:57], v[18:33]
	v_add_f32_e32 v110, v110, v126
	v_add_f32_e32 v110, v110, v127
	v_add_f32_e32 v110, v110, v128
	v_add_f32_e32 v110, v110, v129
	s_waitcnt lgkmcnt(1)
	v_mfma_f32_32x32x16_bf16 v[2:17], v[74:77], v[54:57], v[2:17]
	v_cvt_pk_bf16_f32 v50, v102, v103
	v_cvt_pk_bf16_f32 v51, v104, v105
	v_cvt_pk_bf16_f32 v52, v106, v107
	v_cvt_pk_bf16_f32 v53, v108, v109
	v_add_f32_e32 v110, v110, v203
	v_add_f32_e32 v110, v110, v204
	v_add_f32_e32 v110, v110, v205
	v_add_f32_e32 v110, v110, v206
	s_nop 0
	v_mfma_f32_32x32x16_bf16 v[18:33], v[70:73], v[50:53], v[18:33]
	v_add_f32_e32 v110, v110, v102
	v_add_f32_e32 v110, v110, v103
	v_add_f32_e32 v110, v110, v104
	v_add_f32_e32 v110, v110, v105
	s_waitcnt lgkmcnt(0)
	v_mfma_f32_32x32x16_bf16 v[2:17], v[78:81], v[50:53], v[2:17]
	v_add_f32_e32 v110, v110, v106
	v_add_f32_e32 v110, v110, v107
	v_add_f32_e32 v110, v110, v108
	v_add_f32_e32 v110, v110, v109
	s_setprio 2
	s_waitcnt lgkmcnt(0)
	s_barrier
	ds_read_b128 v[240:243], v165
	ds_read_b128 v[244:247], v165 offset:4608
	ds_read_b128 v[102:105], v165 offset:32
	ds_read_b128 v[106:109], v165 offset:4640
	v_add_f32_e32 v1, v1, v213
	v_exp_f32_e32 v185, v130
	v_exp_f32_e32 v186, v131
	v_exp_f32_e32 v187, v132
	v_exp_f32_e32 v194, v133
	v_exp_f32_e32 v195, v134
	v_exp_f32_e32 v196, v135
	v_exp_f32_e32 v197, v136
	v_exp_f32_e32 v198, v137
	v_exp_f32_e32 v134, v138
	v_exp_f32_e32 v135, v139
	v_exp_f32_e32 v136, v140
	v_exp_f32_e32 v137, v141
	v_exp_f32_e32 v138, v142
	v_exp_f32_e32 v139, v143
	v_exp_f32_e32 v140, v144
	v_exp_f32_e32 v141, v145
	s_waitcnt lgkmcnt(2)
	v_mfma_f32_32x32x16_bf16 v[66:81], v[240:243], v[158:161], v[34:49]
	v_mfma_f32_32x32x16_bf16 v[50:65], v[244:247], v[158:161], v[34:49]
	s_waitcnt lgkmcnt(1)
	v_mfma_f32_32x32x16_bf16 v[66:81], v[102:105], v[154:157], v[66:81]
	v_exp_f32_e32 v142, v82
	v_exp_f32_e32 v143, v83
	v_exp_f32_e32 v144, v84
	v_exp_f32_e32 v145, v85
	v_exp_f32_e32 v199, v86
	v_exp_f32_e32 v200, v87
	v_exp_f32_e32 v201, v88
	v_exp_f32_e32 v202, v89
	s_waitcnt lgkmcnt(0)
	v_mfma_f32_32x32x16_bf16 v[50:65], v[106:109], v[154:157], v[50:65]
	v_exp_f32_e32 v203, v90
	v_exp_f32_e32 v204, v91
	v_exp_f32_e32 v205, v92
	v_exp_f32_e32 v206, v93
	v_exp_f32_e32 v207, v94
	v_exp_f32_e32 v208, v95
	v_exp_f32_e32 v209, v96
	v_exp_f32_e32 v210, v97
	v_add_f32_e32 v1, v1, v110
	v_add_u32_e32 v111, s26, v163
	ds_read_b128 v[240:243], v165 offset:9216
	ds_read_b128 v[244:247], v165 offset:13824
	ds_read_b128 v[82:85], v111 offset:41472
	ds_read_b128 v[86:89], v111 offset:36864
	ds_read_b128 v[90:93], v111 offset:36896
	ds_read_b128 v[94:97], v111 offset:41504
	ds_read_b128 v[98:101], v111 offset:36928
	ds_read_b128 v[102:105], v111 offset:41536
	ds_read_b128 v[106:109], v111 offset:36960
	ds_read_b128 v[110:113], v111 offset:41568
	s_cmp_gt_i32 s24, 2
	s_cselect_b32 s27, -3, 2
	s_add_i32 s27, s27, s24
	s_mulk_i32 s27, 0x2400
	v_add_u32_e32 v250, s27, v182
	s_mov_b32 s27, 0x18950000
	s_waitcnt vmcnt(3)
	ds_write_b128 v182, v[146:149] offset:18432
	s_waitcnt vmcnt(2)
	ds_write_b128 v250, v[150:153] offset:36864
	s_add_i32 s92, s23, -4
	s_lshl_b32 s92, s92, 13
	s_add_u32 vcc_lo, s100, s92
	s_addc_u32 vcc_hi, s101, 0
	global_load_dwordx4 v[126:129], v248, vcc
	s_lshl_b32 s92, s25, 7
	s_add_u32 vcc_lo, s98, s92
	s_addc_u32 vcc_hi, s99, 0
	global_load_dwordx4 v[122:125], v249, vcc
	s_add_i32 s26, s24, 1
	s_setprio 1
	v_cvt_pk_bf16_f32 v130, v185, v186
	v_cvt_pk_bf16_f32 v131, v187, v194
	v_cvt_pk_bf16_f32 v132, v195, v196
	v_cvt_pk_bf16_f32 v133, v197, v198
	s_waitcnt lgkmcnt(8)
	s_nop 0
	v_mfma_f32_32x32x16_bf16 v[18:33], v[86:89], v[130:133], v[18:33]
	v_add_f32_e32 v146, v185, v186
	v_add_f32_e32 v146, v146, v187
	v_add_f32_e32 v146, v146, v194
	s_nop 0
	v_mfma_f32_32x32x16_bf16 v[2:17], v[82:85], v[130:133], v[2:17]
	v_cvt_pk_bf16_f32 v86, v134, v135
	v_cvt_pk_bf16_f32 v87, v136, v137
	v_cvt_pk_bf16_f32 v88, v138, v139
	v_cvt_pk_bf16_f32 v89, v140, v141
	v_add_f32_e32 v146, v146, v195
	v_add_f32_e32 v146, v146, v196
	v_add_f32_e32 v146, v146, v197
	v_add_f32_e32 v146, v146, v198
	s_waitcnt lgkmcnt(7)
	v_mfma_f32_32x32x16_bf16 v[18:33], v[90:93], v[86:89], v[18:33]
	v_add_f32_e32 v146, v146, v134
	v_add_f32_e32 v146, v146, v135
	v_add_f32_e32 v146, v146, v136
	v_add_f32_e32 v146, v146, v137
	s_waitcnt lgkmcnt(6)
	v_mfma_f32_32x32x16_bf16 v[2:17], v[94:97], v[86:89], v[2:17]
	v_cvt_pk_bf16_f32 v82, v142, v143
	v_cvt_pk_bf16_f32 v83, v144, v145
	v_cvt_pk_bf16_f32 v84, v199, v200
	v_cvt_pk_bf16_f32 v85, v201, v202
	v_add_f32_e32 v146, v146, v138
	v_add_f32_e32 v146, v146, v139
	v_add_f32_e32 v146, v146, v140
	v_add_f32_e32 v146, v146, v141
	s_waitcnt lgkmcnt(5)
	v_mfma_f32_32x32x16_bf16 v[18:33], v[98:101], v[82:85], v[18:33]
	v_add_f32_e32 v146, v146, v142
	v_add_f32_e32 v146, v146, v143
	v_add_f32_e32 v146, v146, v144
	v_add_f32_e32 v146, v146, v145
	s_waitcnt lgkmcnt(4)
	v_mfma_f32_32x32x16_bf16 v[2:17], v[102:105], v[82:85], v[2:17]
	v_cvt_pk_bf16_f32 v86, v203, v204
	v_cvt_pk_bf16_f32 v87, v205, v206
	v_cvt_pk_bf16_f32 v88, v207, v208
	v_cvt_pk_bf16_f32 v89, v209, v210
	v_add_f32_e32 v146, v146, v199
	v_add_f32_e32 v146, v146, v200
	v_add_f32_e32 v146, v146, v201
	v_add_f32_e32 v146, v146, v202
	s_waitcnt lgkmcnt(3)
	v_mfma_f32_32x32x16_bf16 v[18:33], v[106:109], v[86:89], v[18:33]
	v_add_f32_e32 v146, v146, v203
	v_add_f32_e32 v146, v146, v204
	v_add_f32_e32 v146, v146, v205
	v_add_f32_e32 v146, v146, v206
	s_waitcnt lgkmcnt(2)
	v_mfma_f32_32x32x16_bf16 v[2:17], v[110:113], v[86:89], v[2:17]
	v_add_f32_e32 v146, v146, v207
	v_add_f32_e32 v146, v146, v208
	v_add_f32_e32 v146, v146, v209
	v_add_f32_e32 v146, v146, v210
	s_setprio 0
	ds_read_b128 v[130:133], v165 offset:9248
	ds_read_b128 v[138:141], v165 offset:13856
	s_cmp_lg_u32 s24, 4
	s_cselect_b32 s24, s26, 0
	s_waitcnt lgkmcnt(2)
	v_mfma_f32_32x32x16_bf16 v[98:113], v[240:243], v[158:161], v[34:49]
	v_exp_f32_e32 v142, v66
	v_exp_f32_e32 v143, v67
	v_exp_f32_e32 v144, v68
	v_exp_f32_e32 v145, v69
	v_exp_f32_e32 v147, v70
	v_exp_f32_e32 v148, v71
	v_exp_f32_e32 v149, v72
	v_exp_f32_e32 v150, v73
	s_waitcnt lgkmcnt(1)
	v_mfma_f32_32x32x16_bf16 v[82:97], v[244:247], v[158:161], v[34:49]
	v_exp_f32_e32 v151, v74
	v_exp_f32_e32 v152, v75
	v_exp_f32_e32 v153, v76
	v_exp_f32_e32 v178, v77
	v_exp_f32_e32 v134, v78
	v_exp_f32_e32 v135, v79
	v_exp_f32_e32 v136, v80
	v_exp_f32_e32 v137, v81
	v_mfma_f32_32x32x16_bf16 v[98:113], v[130:133], v[154:157], v[98:113]
	v_exp_f32_e32 v179, v50
	v_exp_f32_e32 v185, v51
	v_exp_f32_e32 v186, v52
	v_exp_f32_e32 v187, v53
	v_exp_f32_e32 v194, v54
	v_exp_f32_e32 v195, v55
	v_exp_f32_e32 v196, v56
	v_exp_f32_e32 v197, v57
	s_waitcnt lgkmcnt(0)
	v_mfma_f32_32x32x16_bf16 v[82:97], v[138:141], v[154:157], v[82:97]
	v_exp_f32_e32 v198, v58
	v_exp_f32_e32 v199, v59
	v_exp_f32_e32 v200, v60
	v_exp_f32_e32 v201, v61
	v_exp_f32_e32 v138, v62
	v_exp_f32_e32 v139, v63
	v_exp_f32_e32 v140, v64
	v_exp_f32_e32 v141, v65
	s_cmp_gt_i32 s24, 2
	s_cselect_b32 s25, -3, 2
	s_add_i32 s25, s25, s24
	s_mulk_i32 s25, 0x2400
	v_add_u32_e32 v50, s25, v182
	s_add_i32 s25, s24, 1
	s_cmp_lg_u32 s24, 4
	s_cselect_b32 s25, s25, 0
	s_add_i32 s24, s23, -3
	s_min_u32 s26, s24, s13
	s_lshl_b32 s92, s26, 13
	s_waitcnt vmcnt(3)
	ds_write_b128 v182, v[118:121] offset:27648
	s_waitcnt vmcnt(2)
	ds_write_b128 v50, v[114:117] offset:36864
	s_add_u32 vcc_lo, s100, s92
	s_addc_u32 vcc_hi, s101, 0
	global_load_dwordx4 v[118:121], v248, vcc
	s_add_i32 s92, s23, -4
	s_lshl_b32 s92, s92, 7
	s_add_u32 vcc_lo, s98, s92
	s_addc_u32 vcc_hi, s99, 0
	global_load_dwordx4 v[114:117], v249, vcc
	s_mul_i32 s27, s25, 0x2400
	s_add_i32 s28, s27, 0xffffdc00
	s_cmp_lg_u32 s25, 0
	s_cselect_b32 s28, s28, 0x9000
	v_add_u32_e32 v78, s28, v163
	ds_read_b128 v[50:53], v78 offset:36864
	ds_read_b128 v[54:57], v78 offset:36896
	ds_read_b128 v[58:61], v78 offset:41472
	ds_read_b128 v[62:65], v78 offset:41504
	ds_read_b128 v[66:69], v78 offset:36928
	ds_read_b128 v[70:73], v78 offset:36960
	ds_read_b128 v[74:77], v78 offset:41536
	ds_read_b128 v[78:81], v78 offset:41568
	s_setprio 3
	v_cvt_pk_bf16_f32 v130, v142, v143
	v_cvt_pk_bf16_f32 v131, v144, v145
	v_cvt_pk_bf16_f32 v132, v147, v148
	v_cvt_pk_bf16_f32 v133, v149, v150
	s_waitcnt lgkmcnt(7)
	s_nop 0
	v_mfma_f32_32x32x16_bf16 v[18:33], v[50:53], v[130:133], v[18:33]
	v_add_f32_e32 v176, v142, v143
	v_add_f32_e32 v176, v176, v144
	v_add_f32_e32 v176, v176, v145
	s_waitcnt lgkmcnt(5)
	v_mfma_f32_32x32x16_bf16 v[2:17], v[58:61], v[130:133], v[2:17]
	v_cvt_pk_bf16_f32 v50, v151, v152
	v_cvt_pk_bf16_f32 v51, v153, v178
	v_cvt_pk_bf16_f32 v52, v134, v135
	v_cvt_pk_bf16_f32 v53, v136, v137
	v_add_f32_e32 v176, v176, v147
	v_add_f32_e32 v176, v176, v148
	v_add_f32_e32 v176, v176, v149
	v_add_f32_e32 v176, v176, v150
	s_nop 0
	v_mfma_f32_32x32x16_bf16 v[18:33], v[54:57], v[50:53], v[18:33]
	v_add_f32_e32 v176, v176, v151
	v_add_f32_e32 v176, v176, v152
	v_add_f32_e32 v176, v176, v153
	v_add_f32_e32 v176, v176, v178
	s_waitcnt lgkmcnt(4)
	v_mfma_f32_32x32x16_bf16 v[2:17], v[62:65], v[50:53], v[2:17]
	v_cvt_pk_bf16_f32 v54, v179, v185
	v_cvt_pk_bf16_f32 v55, v186, v187
	v_cvt_pk_bf16_f32 v56, v194, v195
	v_cvt_pk_bf16_f32 v57, v196, v197
	v_add_f32_e32 v176, v176, v134
	v_add_f32_e32 v176, v176, v135
	v_add_f32_e32 v176, v176, v136
	v_add_f32_e32 v176, v176, v137
	s_waitcnt lgkmcnt(3)
	v_mfma_f32_32x32x16_bf16 v[18:33], v[66:69], v[54:57], v[18:33]
	v_add_f32_e32 v176, v176, v179
	v_add_f32_e32 v176, v176, v185
	v_add_f32_e32 v176, v176, v186
	v_add_f32_e32 v176, v176, v187
	s_waitcnt lgkmcnt(1)
	v_mfma_f32_32x32x16_bf16 v[2:17], v[74:77], v[54:57], v[2:17]
	v_cvt_pk_bf16_f32 v50, v198, v199
	v_cvt_pk_bf16_f32 v51, v200, v201
	v_cvt_pk_bf16_f32 v52, v138, v139
	v_cvt_pk_bf16_f32 v53, v140, v141
	v_add_f32_e32 v176, v176, v194
	v_add_f32_e32 v176, v176, v195
	v_add_f32_e32 v176, v176, v196
	v_add_f32_e32 v176, v176, v197
	s_nop 0
	v_mfma_f32_32x32x16_bf16 v[18:33], v[70:73], v[50:53], v[18:33]
	v_add_f32_e32 v176, v176, v198
	v_add_f32_e32 v176, v176, v199
	v_add_f32_e32 v176, v176, v200
	v_add_f32_e32 v176, v176, v201
	s_waitcnt lgkmcnt(0)
	v_mfma_f32_32x32x16_bf16 v[2:17], v[78:81], v[50:53], v[2:17]
	v_add_f32_e32 v176, v176, v138
	v_add_f32_e32 v176, v176, v139
	v_add_f32_e32 v176, v176, v140
	v_add_f32_e32 v176, v176, v141
	s_setprio 2
	s_waitcnt lgkmcnt(0)
	s_barrier
	ds_read_b128 v[240:243], v165 offset:18432
	ds_read_b128 v[244:247], v165 offset:23040
	ds_read_b128 v[134:137], v165 offset:18464
	ds_read_b128 v[138:141], v165 offset:23072
	v_add_f32_e32 v1, v1, v146
	v_exp_f32_e32 v142, v98
	v_exp_f32_e32 v143, v99
	v_exp_f32_e32 v144, v100
	v_exp_f32_e32 v145, v101
	v_exp_f32_e32 v146, v102
	v_exp_f32_e32 v147, v103
	v_exp_f32_e32 v148, v104
	v_exp_f32_e32 v149, v105
	v_exp_f32_e32 v150, v106
	v_exp_f32_e32 v151, v107
	v_exp_f32_e32 v152, v108
	v_exp_f32_e32 v153, v109
	v_exp_f32_e32 v177, v110
	v_exp_f32_e32 v178, v111
	v_exp_f32_e32 v179, v112
	v_exp_f32_e32 v185, v113
	s_waitcnt lgkmcnt(2)
	v_mfma_f32_32x32x16_bf16 v[66:81], v[240:243], v[158:161], v[34:49]
	v_mfma_f32_32x32x16_bf16 v[50:65], v[244:247], v[158:161], v[34:49]
	s_waitcnt lgkmcnt(1)
	v_mfma_f32_32x32x16_bf16 v[66:81], v[134:137], v[154:157], v[66:81]
	v_exp_f32_e32 v186, v82
	v_exp_f32_e32 v187, v83
	v_exp_f32_e32 v194, v84
	v_exp_f32_e32 v195, v85
	v_exp_f32_e32 v134, v86
	v_exp_f32_e32 v135, v87
	v_exp_f32_e32 v136, v88
	v_exp_f32_e32 v137, v89
	s_waitcnt lgkmcnt(0)
	v_mfma_f32_32x32x16_bf16 v[50:65], v[138:141], v[154:157], v[50:65]
	v_exp_f32_e32 v196, v90
	v_exp_f32_e32 v197, v91
	v_exp_f32_e32 v198, v92
	v_exp_f32_e32 v199, v93
	v_exp_f32_e32 v138, v94
	v_exp_f32_e32 v139, v95
	v_exp_f32_e32 v140, v96
	v_exp_f32_e32 v141, v97
	s_cmp_gt_i32 s25, 2
	s_cselect_b32 s28, -3, 2
	s_waitcnt vmcnt(3)
	ds_write_b128 v182, v[126:129]
	s_add_i32 s28, s28, s25
	v_add_u32_e32 v126, s27, v163
	s_add_i32 s27, s23, -2
	s_mulk_i32 s28, 0x2400
	s_min_u32 s27, s27, s13
	v_add_u32_e32 v82, s28, v182
	s_lshl_b32 s92, s27, 13
	s_waitcnt vmcnt(2)
	ds_write_b128 v82, v[122:125] offset:36864
	ds_read_b128 v[240:243], v165 offset:27648
	ds_read_b128 v[244:247], v165 offset:32256
	ds_read_b128 v[82:85], v126 offset:41472
	ds_read_b128 v[86:89], v126 offset:36864
	ds_read_b128 v[90:93], v126 offset:36896
	ds_read_b128 v[94:97], v126 offset:41504
	ds_read_b128 v[106:109], v126 offset:36928
	ds_read_b128 v[110:113], v126 offset:41536
	ds_read_b128 v[122:125], v126 offset:36960
	ds_read_b128 v[126:129], v126 offset:41568
	s_add_u32 vcc_lo, s100, s92
	s_addc_u32 vcc_hi, s101, 0
	global_load_dwordx4 v[98:101], v248, vcc
	s_lshl_b32 s92, s26, 7
	s_add_u32 vcc_lo, s98, s92
	s_addc_u32 vcc_hi, s99, 0
	global_load_dwordx4 v[102:105], v249, vcc
	v_add_f32_e32 v1, v1, v176
	s_add_i32 s28, s25, 1
	s_setprio 1
	v_cvt_pk_bf16_f32 v130, v142, v143
	v_cvt_pk_bf16_f32 v131, v144, v145
	v_cvt_pk_bf16_f32 v132, v146, v147
	v_cvt_pk_bf16_f32 v133, v148, v149
	s_waitcnt lgkmcnt(6)
	s_nop 0
	v_mfma_f32_32x32x16_bf16 v[18:33], v[86:89], v[130:133], v[18:33]
	v_add_f32_e32 v176, v142, v143
	v_add_f32_e32 v176, v176, v144
	v_add_f32_e32 v176, v176, v145
	s_nop 0
	v_mfma_f32_32x32x16_bf16 v[2:17], v[82:85], v[130:133], v[2:17]
	v_cvt_pk_bf16_f32 v86, v150, v151
	v_cvt_pk_bf16_f32 v87, v152, v153
	v_cvt_pk_bf16_f32 v88, v177, v178
	v_cvt_pk_bf16_f32 v89, v179, v185
	v_add_f32_e32 v176, v176, v146
	v_add_f32_e32 v176, v176, v147
	v_add_f32_e32 v176, v176, v148
	v_add_f32_e32 v176, v176, v149
	s_waitcnt lgkmcnt(5)
	v_mfma_f32_32x32x16_bf16 v[18:33], v[90:93], v[86:89], v[18:33]
	v_add_f32_e32 v176, v176, v150
	v_add_f32_e32 v176, v176, v151
	v_add_f32_e32 v176, v176, v152
	v_add_f32_e32 v176, v176, v153
	s_waitcnt lgkmcnt(4)
	v_mfma_f32_32x32x16_bf16 v[2:17], v[94:97], v[86:89], v[2:17]
	v_cvt_pk_bf16_f32 v82, v186, v187
	v_cvt_pk_bf16_f32 v83, v194, v195
	v_cvt_pk_bf16_f32 v84, v134, v135
	v_cvt_pk_bf16_f32 v85, v136, v137
	v_add_f32_e32 v176, v176, v177
	v_add_f32_e32 v176, v176, v178
	v_add_f32_e32 v176, v176, v179
	v_add_f32_e32 v176, v176, v185
	s_waitcnt lgkmcnt(3)
	v_mfma_f32_32x32x16_bf16 v[18:33], v[106:109], v[82:85], v[18:33]
	v_add_f32_e32 v176, v176, v186
	v_add_f32_e32 v176, v176, v187
	v_add_f32_e32 v176, v176, v194
	v_add_f32_e32 v176, v176, v195
	s_waitcnt lgkmcnt(2)
	v_mfma_f32_32x32x16_bf16 v[2:17], v[110:113], v[82:85], v[2:17]
	v_cvt_pk_bf16_f32 v86, v196, v197
	v_cvt_pk_bf16_f32 v87, v198, v199
	v_cvt_pk_bf16_f32 v88, v138, v139
	v_cvt_pk_bf16_f32 v89, v140, v141
	v_add_f32_e32 v176, v176, v134
	v_add_f32_e32 v176, v176, v135
	v_add_f32_e32 v176, v176, v136
	v_add_f32_e32 v176, v176, v137
	s_waitcnt lgkmcnt(1)
	v_mfma_f32_32x32x16_bf16 v[18:33], v[122:125], v[86:89], v[18:33]
	v_add_f32_e32 v176, v176, v196
	v_add_f32_e32 v176, v176, v197
	v_add_f32_e32 v176, v176, v198
	v_add_f32_e32 v176, v176, v199
	s_waitcnt lgkmcnt(0)
	v_mfma_f32_32x32x16_bf16 v[2:17], v[126:129], v[86:89], v[2:17]
	v_add_f32_e32 v176, v176, v138
	v_add_f32_e32 v176, v176, v139
	v_add_f32_e32 v176, v176, v140
	v_add_f32_e32 v176, v176, v141
	s_setprio 0
	ds_read_b128 v[106:109], v165 offset:27680
	ds_read_b128 v[122:125], v165 offset:32288
	s_cmp_lg_u32 s25, 4
	s_cselect_b32 s25, s28, 0
	s_waitcnt lgkmcnt(2)
	v_mfma_f32_32x32x16_bf16 v[138:153], v[240:243], v[158:161], v[34:49]
	v_exp_f32_e32 v126, v66
	v_exp_f32_e32 v127, v67
	v_exp_f32_e32 v128, v68
	v_exp_f32_e32 v129, v69
	v_exp_f32_e32 v130, v70
	v_exp_f32_e32 v131, v71
	v_exp_f32_e32 v132, v72
	v_exp_f32_e32 v133, v73
	s_waitcnt lgkmcnt(1)
	v_mfma_f32_32x32x16_bf16 v[82:97], v[244:247], v[158:161], v[34:49]
	v_exp_f32_e32 v134, v74
	v_exp_f32_e32 v135, v75
	v_exp_f32_e32 v136, v76
	v_exp_f32_e32 v137, v77
	v_exp_f32_e32 v177, v78
	v_exp_f32_e32 v178, v79
	v_exp_f32_e32 v179, v80
	v_exp_f32_e32 v185, v81
	v_mfma_f32_32x32x16_bf16 v[138:153], v[106:109], v[154:157], v[138:153]
	v_exp_f32_e32 v80, v50
	v_exp_f32_e32 v81, v51
	v_exp_f32_e32 v186, v52
	v_exp_f32_e32 v187, v53
	v_exp_f32_e32 v194, v54
	v_exp_f32_e32 v195, v55
	v_exp_f32_e32 v196, v56
	v_exp_f32_e32 v197, v57
	s_waitcnt lgkmcnt(0)
	v_mfma_f32_32x32x16_bf16 v[82:97], v[122:125], v[154:157], v[82:97]
	v_exp_f32_e32 v198, v58
	v_exp_f32_e32 v199, v59
	v_exp_f32_e32 v200, v60
	v_exp_f32_e32 v201, v61
	v_exp_f32_e32 v122, v62
	v_exp_f32_e32 v123, v63
	v_exp_f32_e32 v124, v64
	v_exp_f32_e32 v125, v65
	s_cmp_gt_i32 s25, 2
	s_cselect_b32 s26, -3, 2
	s_add_i32 s26, s26, s25
	s_mulk_i32 s26, 0x2400
	v_add_u32_e32 v50, s26, v182
	s_add_i32 s26, s25, 1
	s_cmp_lg_u32 s25, 4
	s_cselect_b32 s25, s26, 0
	s_add_i32 s26, s23, -1
	s_min_u32 s26, s26, s13
	s_lshl_b32 s92, s26, 13
	s_waitcnt vmcnt(3)
	ds_write_b128 v182, v[118:121] offset:9216
	s_waitcnt vmcnt(2)
	ds_write_b128 v50, v[114:117] offset:36864
	s_add_u32 vcc_lo, s100, s92
	s_addc_u32 vcc_hi, s101, 0
	global_load_dwordx4 v[56:59], v248, vcc
	s_lshl_b32 s92, s27, 7
	s_add_u32 vcc_lo, s98, s92
	s_addc_u32 vcc_hi, s99, 0
	global_load_dwordx4 v[52:55], v249, vcc
	s_nop 0
	s_mul_i32 s27, s25, 0x2400
	s_add_i32 s28, s27, 0xffffdc00
	s_cmp_lg_u32 s25, 0
	s_cselect_b32 s28, s28, 0x9000
	v_add_u32_e32 v50, s28, v163
	ds_read_b128 v[60:63], v50 offset:36864
	ds_read_b128 v[64:67], v50 offset:36896
	ds_read_b128 v[68:71], v50 offset:41472
	ds_read_b128 v[72:75], v50 offset:41504
	ds_read_b128 v[76:79], v50 offset:36928
	ds_read_b128 v[106:109], v50 offset:36960
	ds_read_b128 v[110:113], v50 offset:41536
	ds_read_b128 v[114:117], v50 offset:41568
	s_setprio 3
	v_cvt_pk_bf16_f32 v118, v126, v127
	v_cvt_pk_bf16_f32 v119, v128, v129
	v_cvt_pk_bf16_f32 v120, v130, v131
	v_cvt_pk_bf16_f32 v121, v132, v133
	s_waitcnt lgkmcnt(7)
	s_nop 0
	v_mfma_f32_32x32x16_bf16 v[18:33], v[60:63], v[118:121], v[18:33]
	v_add_f32_e32 v50, v126, v127
	v_add_f32_e32 v50, v50, v128
	v_add_f32_e32 v50, v50, v129
	s_waitcnt lgkmcnt(5)
	v_mfma_f32_32x32x16_bf16 v[2:17], v[68:71], v[118:121], v[2:17]
	v_cvt_pk_bf16_f32 v60, v134, v135
	v_cvt_pk_bf16_f32 v61, v136, v137
	v_cvt_pk_bf16_f32 v62, v177, v178
	v_cvt_pk_bf16_f32 v63, v179, v185
	v_add_f32_e32 v50, v50, v130
	v_add_f32_e32 v50, v50, v131
	v_add_f32_e32 v50, v50, v132
	v_add_f32_e32 v50, v50, v133
	s_nop 0
	v_mfma_f32_32x32x16_bf16 v[18:33], v[64:67], v[60:63], v[18:33]
	v_add_f32_e32 v50, v50, v134
	v_add_f32_e32 v50, v50, v135
	v_add_f32_e32 v50, v50, v136
	v_add_f32_e32 v50, v50, v137
	s_waitcnt lgkmcnt(4)
	v_mfma_f32_32x32x16_bf16 v[2:17], v[72:75], v[60:63], v[2:17]
	v_cvt_pk_bf16_f32 v64, v80, v81
	v_cvt_pk_bf16_f32 v65, v186, v187
	v_cvt_pk_bf16_f32 v66, v194, v195
	v_cvt_pk_bf16_f32 v67, v196, v197
	v_add_f32_e32 v50, v50, v177
	v_add_f32_e32 v50, v50, v178
	v_add_f32_e32 v50, v50, v179
	v_add_f32_e32 v50, v50, v185
	s_waitcnt lgkmcnt(3)
	v_mfma_f32_32x32x16_bf16 v[18:33], v[76:79], v[64:67], v[18:33]
	v_add_f32_e32 v50, v50, v80
	v_add_f32_e32 v50, v50, v81
	v_add_f32_e32 v50, v50, v186
	v_add_f32_e32 v50, v50, v187
	s_waitcnt lgkmcnt(1)
	v_mfma_f32_32x32x16_bf16 v[2:17], v[110:113], v[64:67], v[2:17]
	v_cvt_pk_bf16_f32 v60, v198, v199
	v_cvt_pk_bf16_f32 v61, v200, v201
	v_cvt_pk_bf16_f32 v62, v122, v123
	v_cvt_pk_bf16_f32 v63, v124, v125
	v_add_f32_e32 v50, v50, v194
	v_add_f32_e32 v50, v50, v195
	v_add_f32_e32 v50, v50, v196
	v_add_f32_e32 v50, v50, v197
	s_nop 0
	v_mfma_f32_32x32x16_bf16 v[18:33], v[106:109], v[60:63], v[18:33]
	v_add_f32_e32 v50, v50, v198
	v_add_f32_e32 v50, v50, v199
	v_add_f32_e32 v50, v50, v200
	v_add_f32_e32 v50, v50, v201
	s_waitcnt lgkmcnt(0)
	v_mfma_f32_32x32x16_bf16 v[2:17], v[114:117], v[60:63], v[2:17]
	v_add_f32_e32 v50, v50, v122
	v_add_f32_e32 v50, v50, v123
	v_add_f32_e32 v50, v50, v124
	v_add_f32_e32 v50, v50, v125
	s_setprio 2
	s_waitcnt lgkmcnt(0)
	s_barrier
	ds_read_b128 v[240:243], v165
	ds_read_b128 v[244:247], v165 offset:4608
	ds_read_b128 v[68:71], v165 offset:32
	ds_read_b128 v[72:75], v165 offset:4640
	v_add_f32_e32 v1, v1, v176
	v_exp_f32_e32 v176, v138
	v_exp_f32_e32 v177, v139
	v_exp_f32_e32 v178, v140
	v_exp_f32_e32 v179, v141
	v_exp_f32_e32 v185, v142
	v_exp_f32_e32 v186, v143
	v_exp_f32_e32 v187, v144
	v_exp_f32_e32 v194, v145
	v_exp_f32_e32 v195, v146
	v_exp_f32_e32 v196, v147
	v_exp_f32_e32 v197, v148
	v_exp_f32_e32 v198, v149
	v_exp_f32_e32 v146, v150
	v_exp_f32_e32 v147, v151
	v_exp_f32_e32 v148, v152
	v_exp_f32_e32 v149, v153
	s_waitcnt lgkmcnt(2)
	v_mfma_f32_32x32x16_bf16 v[122:137], v[240:243], v[158:161], v[34:49]
	v_mfma_f32_32x32x16_bf16 v[106:121], v[244:247], v[158:161], v[34:49]
	s_waitcnt lgkmcnt(1)
	v_mfma_f32_32x32x16_bf16 v[122:137], v[68:71], v[154:157], v[122:137]
	v_exp_f32_e32 v150, v82
	v_exp_f32_e32 v151, v83
	v_exp_f32_e32 v152, v84
	v_exp_f32_e32 v153, v85
	v_exp_f32_e32 v199, v86
	v_exp_f32_e32 v200, v87
	v_exp_f32_e32 v201, v88
	v_exp_f32_e32 v202, v89
	s_waitcnt lgkmcnt(0)
	v_mfma_f32_32x32x16_bf16 v[106:121], v[72:75], v[154:157], v[106:121]
	v_exp_f32_e32 v203, v90
	v_exp_f32_e32 v204, v91
	v_exp_f32_e32 v205, v92
	v_exp_f32_e32 v206, v93
	v_exp_f32_e32 v207, v94
	v_exp_f32_e32 v208, v95
	v_exp_f32_e32 v209, v96
	v_exp_f32_e32 v210, v97
	v_add_u32_e32 v88, s27, v163
	ds_read_b128 v[240:243], v165 offset:9216
	ds_read_b128 v[244:247], v165 offset:13824
	ds_read_b128 v[60:63], v88 offset:41472
	ds_read_b128 v[64:67], v88 offset:36864
	ds_read_b128 v[68:71], v88 offset:36896
	ds_read_b128 v[72:75], v88 offset:41504
	ds_read_b128 v[76:79], v88 offset:36928
	ds_read_b128 v[80:83], v88 offset:41536
	ds_read_b128 v[84:87], v88 offset:36960
	ds_read_b128 v[88:91], v88 offset:41568
	s_cmp_gt_i32 s25, 2
	s_cselect_b32 s28, -3, 2
	s_add_i32 s28, s28, s25
	s_mulk_i32 s28, 0x2400
	s_min_u32 s27, s23, s13
	v_add_u32_e32 v51, s28, v182
	s_lshl_b32 s92, s27, 13
	s_waitcnt vmcnt(3)
	ds_write_b128 v182, v[98:101] offset:18432
	s_waitcnt vmcnt(2)
	ds_write_b128 v51, v[102:105] offset:36864
	v_add_f32_e32 v1, v1, v50
	s_add_u32 vcc_lo, s100, s92
	s_addc_u32 vcc_hi, s101, 0
	global_load_dwordx4 v[138:141], v248, vcc
	s_lshl_b32 s92, s26, 7
	s_add_u32 vcc_lo, s98, s92
	s_addc_u32 vcc_hi, s99, 0
	global_load_dwordx4 v[142:145], v249, vcc
	s_setprio 1
	v_mov_b32_e32 v51, v122
	v_cvt_pk_bf16_f32 v92, v176, v177
	v_cvt_pk_bf16_f32 v93, v178, v179
	v_cvt_pk_bf16_f32 v94, v185, v186
	v_cvt_pk_bf16_f32 v95, v187, v194
	s_waitcnt lgkmcnt(8)
	s_nop 0
	v_mfma_f32_32x32x16_bf16 v[18:33], v[64:67], v[92:95], v[18:33]
	v_max3_f32 v51, v51, v123, v124
	v_max3_f32 v51, v51, v125, v126
	v_add_f32_e32 v50, v176, v177
	v_add_f32_e32 v50, v50, v178
	v_add_f32_e32 v50, v50, v179
	s_nop 0
	v_mfma_f32_32x32x16_bf16 v[2:17], v[60:63], v[92:95], v[2:17]
	v_cvt_pk_bf16_f32 v64, v195, v196
	v_cvt_pk_bf16_f32 v65, v197, v198
	v_cvt_pk_bf16_f32 v66, v146, v147
	v_cvt_pk_bf16_f32 v67, v148, v149
	v_max3_f32 v51, v51, v127, v128
	v_max3_f32 v51, v51, v129, v130
	v_add_f32_e32 v50, v50, v185
	v_add_f32_e32 v50, v50, v186
	v_add_f32_e32 v50, v50, v187
	v_add_f32_e32 v50, v50, v194
	s_waitcnt lgkmcnt(7)
	v_mfma_f32_32x32x16_bf16 v[18:33], v[68:71], v[64:67], v[18:33]
	v_max3_f32 v51, v51, v131, v132
	v_max3_f32 v51, v51, v133, v134
	v_add_f32_e32 v50, v50, v195
	v_add_f32_e32 v50, v50, v196
	v_add_f32_e32 v50, v50, v197
	v_add_f32_e32 v50, v50, v198
	s_waitcnt lgkmcnt(6)
	v_mfma_f32_32x32x16_bf16 v[2:17], v[72:75], v[64:67], v[2:17]
	v_cvt_pk_bf16_f32 v60, v150, v151
	v_cvt_pk_bf16_f32 v61, v152, v153
	v_cvt_pk_bf16_f32 v62, v199, v200
	v_cvt_pk_bf16_f32 v63, v201, v202
	v_max3_f32 v51, v51, v135, v136
	v_max3_f32 v51, v51, v137, v106
	v_add_f32_e32 v50, v50, v146
	v_add_f32_e32 v50, v50, v147
	v_add_f32_e32 v50, v50, v148
	v_add_f32_e32 v50, v50, v149
	s_waitcnt lgkmcnt(5)
	v_mfma_f32_32x32x16_bf16 v[18:33], v[76:79], v[60:63], v[18:33]
	v_max3_f32 v51, v51, v107, v108
	v_max3_f32 v51, v51, v109, v110
	v_add_f32_e32 v50, v50, v150
	v_add_f32_e32 v50, v50, v151
	v_add_f32_e32 v50, v50, v152
	v_add_f32_e32 v50, v50, v153
	s_waitcnt lgkmcnt(4)
	v_mfma_f32_32x32x16_bf16 v[2:17], v[80:83], v[60:63], v[2:17]
	v_cvt_pk_bf16_f32 v64, v203, v204
	v_cvt_pk_bf16_f32 v65, v205, v206
	v_cvt_pk_bf16_f32 v66, v207, v208
	v_cvt_pk_bf16_f32 v67, v209, v210
	v_max3_f32 v51, v51, v111, v112
	v_max3_f32 v51, v51, v113, v114
	v_add_f32_e32 v50, v50, v199
	v_add_f32_e32 v50, v50, v200
	v_add_f32_e32 v50, v50, v201
	v_add_f32_e32 v50, v50, v202
	s_waitcnt lgkmcnt(3)
	v_mfma_f32_32x32x16_bf16 v[18:33], v[84:87], v[64:67], v[18:33]
	v_max3_f32 v51, v51, v115, v116
	v_max3_f32 v51, v51, v117, v118
	v_add_f32_e32 v50, v50, v203
	v_add_f32_e32 v50, v50, v204
	v_add_f32_e32 v50, v50, v205
	v_add_f32_e32 v50, v50, v206
	s_waitcnt lgkmcnt(2)
	v_mfma_f32_32x32x16_bf16 v[2:17], v[88:91], v[64:67], v[2:17]
	v_max3_f32 v51, v51, v119, v120
	v_max3_f32 v51, v51, v121, v121
	v_add_f32_e32 v50, v50, v207
	v_add_f32_e32 v50, v50, v208
	v_add_f32_e32 v50, v50, v209
	v_add_f32_e32 v50, v50, v210
	s_setprio 0
	ds_read_b128 v[146:149], v165 offset:9248
	ds_read_b128 v[60:63], v165 offset:13856
	v_add_f32_e32 v50, v1, v50
	v_mov_b32_e32 v1, v51
	s_nop 1
	v_permlane32_swap_b32_e32 v51, v1
	v_max_f32_e32 v1, v1, v1
	v_max_f32_e32 v51, v51, v51
	v_max_f32_e32 v1, v51, v1
	v_cmp_lt_f32_e32 vcc, s52, v1
	s_cbranch_vccz .LBB0_643
	v_max_f32_e32 v1, v1, v1
	v_max_f32_e32 v68, 0, v1
	v_add_f32_e32 v183, v183, v68
	v_xor_b32_e32 v34, 0x80000000, v183
	v_pk_add_f32 v[122:123], v[122:123], v[68:69] op_sel_hi:[1,0] neg_lo:[0,1] neg_hi:[0,1]
	v_pk_add_f32 v[106:107], v[106:107], v[68:69] op_sel_hi:[1,0] neg_lo:[0,1] neg_hi:[0,1]
	v_pk_add_f32 v[124:125], v[124:125], v[68:69] op_sel_hi:[1,0] neg_lo:[0,1] neg_hi:[0,1]
	v_pk_add_f32 v[108:109], v[108:109], v[68:69] op_sel_hi:[1,0] neg_lo:[0,1] neg_hi:[0,1]
	v_pk_add_f32 v[126:127], v[126:127], v[68:69] op_sel_hi:[1,0] neg_lo:[0,1] neg_hi:[0,1]
	v_pk_add_f32 v[110:111], v[110:111], v[68:69] op_sel_hi:[1,0] neg_lo:[0,1] neg_hi:[0,1]
	v_pk_add_f32 v[128:129], v[128:129], v[68:69] op_sel_hi:[1,0] neg_lo:[0,1] neg_hi:[0,1]
	v_pk_add_f32 v[112:113], v[112:113], v[68:69] op_sel_hi:[1,0] neg_lo:[0,1] neg_hi:[0,1]
	v_pk_add_f32 v[130:131], v[130:131], v[68:69] op_sel_hi:[1,0] neg_lo:[0,1] neg_hi:[0,1]
	v_pk_add_f32 v[114:115], v[114:115], v[68:69] op_sel_hi:[1,0] neg_lo:[0,1] neg_hi:[0,1]
	v_pk_add_f32 v[132:133], v[132:133], v[68:69] op_sel_hi:[1,0] neg_lo:[0,1] neg_hi:[0,1]
	v_pk_add_f32 v[116:117], v[116:117], v[68:69] op_sel_hi:[1,0] neg_lo:[0,1] neg_hi:[0,1]
	v_pk_add_f32 v[134:135], v[134:135], v[68:69] op_sel_hi:[1,0] neg_lo:[0,1] neg_hi:[0,1]
	v_pk_add_f32 v[118:119], v[118:119], v[68:69] op_sel_hi:[1,0] neg_lo:[0,1] neg_hi:[0,1]
	v_pk_add_f32 v[136:137], v[136:137], v[68:69] op_sel_hi:[1,0] neg_lo:[0,1] neg_hi:[0,1]
	v_pk_add_f32 v[120:121], v[120:121], v[68:69] op_sel_hi:[1,0] neg_lo:[0,1] neg_hi:[0,1]
	v_exp_f32_e64 v68, -v68
	v_mov_b32_e32 v35, v34
	v_mov_b32_e32 v36, v34
	v_mov_b32_e32 v37, v34
	v_mov_b32_e32 v38, v34
	v_mov_b32_e32 v39, v34
	v_mov_b32_e32 v40, v34
	v_mov_b32_e32 v41, v34
	v_mov_b32_e32 v42, v34
	v_mov_b32_e32 v43, v34
	v_mov_b32_e32 v44, v34
	v_mov_b32_e32 v45, v34
	v_mov_b32_e32 v46, v34
	v_mov_b32_e32 v47, v34
	v_mov_b32_e32 v48, v34
	v_mov_b32_e32 v49, v34
	s_nop 11
	v_pk_mul_f32 v[32:33], v[32:33], v[68:69] op_sel_hi:[1,0]
	v_pk_mul_f32 v[30:31], v[30:31], v[68:69] op_sel_hi:[1,0]
	v_pk_mul_f32 v[28:29], v[28:29], v[68:69] op_sel_hi:[1,0]
	v_pk_mul_f32 v[26:27], v[26:27], v[68:69] op_sel_hi:[1,0]
	v_pk_mul_f32 v[24:25], v[24:25], v[68:69] op_sel_hi:[1,0]
	v_pk_mul_f32 v[22:23], v[22:23], v[68:69] op_sel_hi:[1,0]
	v_pk_mul_f32 v[20:21], v[20:21], v[68:69] op_sel_hi:[1,0]
	v_pk_mul_f32 v[18:19], v[18:19], v[68:69] op_sel_hi:[1,0]
	v_pk_mul_f32 v[16:17], v[16:17], v[68:69] op_sel_hi:[1,0]
	v_pk_mul_f32 v[14:15], v[14:15], v[68:69] op_sel_hi:[1,0]
	v_pk_mul_f32 v[12:13], v[12:13], v[68:69] op_sel_hi:[1,0]
	v_pk_mul_f32 v[10:11], v[10:11], v[68:69] op_sel_hi:[1,0]
	v_pk_mul_f32 v[8:9], v[8:9], v[68:69] op_sel_hi:[1,0]
	v_pk_mul_f32 v[6:7], v[6:7], v[68:69] op_sel_hi:[1,0]
	v_pk_mul_f32 v[4:5], v[4:5], v[68:69] op_sel_hi:[1,0]
	v_pk_mul_f32 v[2:3], v[2:3], v[68:69] op_sel_hi:[1,0]
	v_mul_f32_e32 v50, v50, v68

.LBB0_661:
	s_add_i32 s26, s13, -7
	s_lshl_b32 s92, s26, 13
	s_add_u32 vcc_lo, s100, s92
	s_addc_u32 vcc_hi, s101, 0
	global_load_dwordx4 v[2:5], v248, vcc
	s_add_i32 s26, s13, -8
	s_lshl_b32 s92, s26, 7
	s_add_u32 vcc_lo, s98, s92
	s_addc_u32 vcc_hi, s99, 0
	global_load_dwordx4 v[6:9], v249, vcc
	s_mul_i32 s28, s27, 0x2400
	s_add_i32 s26, s13, -7
	s_add_i32 s29, s28, 0xffffdc00
	s_cmp_lg_u32 s27, 0
	s_cselect_b32 s29, s29, 0x9000
	v_add_u32_e32 v1, s29, v195
	ds_read_b128 v[10:13], v1 offset:36864
	ds_read_b128 v[66:69], v1 offset:36896
	ds_read_b128 v[70:73], v1 offset:41472
	ds_read_b128 v[74:77], v1 offset:41504
	ds_read_b128 v[128:131], v1 offset:36928
	ds_read_b128 v[132:135], v1 offset:36960
	ds_read_b128 v[148:151], v1 offset:41536
	ds_read_b128 v[160:163], v1 offset:41568
	s_setprio 3
	v_cvt_pk_bf16_f32 v210, v116, v117
	v_cvt_pk_bf16_f32 v211, v118, v119
	v_cvt_pk_bf16_f32 v212, v112, v113
	v_cvt_pk_bf16_f32 v213, v114, v115
	s_waitcnt lgkmcnt(7)
	s_nop 0
	v_mfma_f32_32x32x16_bf16 v[16:31], v[10:13], v[210:213], v[16:31]
	v_add_f32_e32 v1, v116, v117
	v_add_f32_e32 v1, v1, v118
	v_add_f32_e32 v1, v1, v119
	s_waitcnt lgkmcnt(5)
	v_mfma_f32_32x32x16_bf16 v[32:47], v[70:73], v[210:213], v[32:47]
	v_cvt_pk_bf16_f32 v10, v187, v186
	v_cvt_pk_bf16_f32 v11, v185, v184
	v_cvt_pk_bf16_f32 v12, v147, v146
	v_cvt_pk_bf16_f32 v13, v145, v144
	v_add_f32_e32 v1, v1, v112
	v_add_f32_e32 v1, v1, v113
	v_add_f32_e32 v1, v1, v114
	v_add_f32_e32 v1, v1, v115
	s_nop 0
	v_mfma_f32_32x32x16_bf16 v[16:31], v[66:69], v[10:13], v[16:31]
	v_add_f32_e32 v1, v1, v187
	v_add_f32_e32 v1, v1, v186
	v_add_f32_e32 v1, v1, v185
	v_add_f32_e32 v1, v1, v184
	s_waitcnt lgkmcnt(4)
	v_mfma_f32_32x32x16_bf16 v[32:47], v[74:77], v[10:13], v[32:47]
	v_cvt_pk_bf16_f32 v66, v143, v142
	v_cvt_pk_bf16_f32 v67, v141, v140
	v_cvt_pk_bf16_f32 v68, v139, v138
	v_cvt_pk_bf16_f32 v69, v137, v136
	v_add_f32_e32 v1, v1, v147
	v_add_f32_e32 v1, v1, v146
	v_add_f32_e32 v1, v1, v145
	v_add_f32_e32 v1, v1, v144
	s_waitcnt lgkmcnt(3)
	v_mfma_f32_32x32x16_bf16 v[16:31], v[128:131], v[66:69], v[16:31]
	v_add_f32_e32 v1, v1, v143
	v_add_f32_e32 v1, v1, v142
	v_add_f32_e32 v1, v1, v141
	v_add_f32_e32 v1, v1, v140
	s_waitcnt lgkmcnt(1)
	v_mfma_f32_32x32x16_bf16 v[32:47], v[148:151], v[66:69], v[32:47]
	v_cvt_pk_bf16_f32 v10, v123, v122
	v_cvt_pk_bf16_f32 v11, v121, v120
	v_cvt_pk_bf16_f32 v12, v127, v126
	v_cvt_pk_bf16_f32 v13, v125, v124
	v_add_f32_e32 v1, v1, v139
	v_add_f32_e32 v1, v1, v138
	v_add_f32_e32 v1, v1, v137
	v_add_f32_e32 v1, v1, v136
	s_nop 0
	v_mfma_f32_32x32x16_bf16 v[16:31], v[132:135], v[10:13], v[16:31]
	v_add_f32_e32 v1, v1, v123
	v_add_f32_e32 v1, v1, v122
	v_add_f32_e32 v1, v1, v121
	v_add_f32_e32 v1, v1, v120
	s_waitcnt lgkmcnt(0)
	v_mfma_f32_32x32x16_bf16 v[32:47], v[160:163], v[10:13], v[32:47]
	v_add_f32_e32 v1, v1, v127
	v_add_f32_e32 v1, v1, v126
	v_add_f32_e32 v1, v1, v125
	v_add_f32_e32 v1, v1, v124
	s_setprio 2
	s_waitcnt lgkmcnt(0)
	s_barrier
	ds_read_b128 v[240:243], v195 offset:18432
	ds_read_b128 v[244:247], v195 offset:23040
	ds_read_b128 v[66:69], v195 offset:18464
	ds_read_b128 v[74:77], v195 offset:23072
	ds_read_b128 v[144:147], v195 offset:18496
	ds_read_b128 v[148:151], v195 offset:18528
	ds_read_b128 v[160:163], v195 offset:23104
	ds_read_b128 v[184:187], v195 offset:23136
	v_exp_f32_e32 v166, v96
	v_exp_f32_e32 v167, v97
	v_exp_f32_e32 v210, v98
	v_exp_f32_e32 v211, v99
	v_exp_f32_e32 v212, v100
	v_exp_f32_e32 v213, v101
	v_exp_f32_e32 v214, v102
	v_exp_f32_e32 v215, v103
	s_waitcnt lgkmcnt(6)
	v_mfma_f32_32x32x16_bf16 v[128:143], v[240:243], v[180:183], v[48:63]
	s_waitcnt lgkmcnt(5)
	v_mfma_f32_32x32x16_bf16 v[112:127], v[244:247], v[180:183], v[48:63]
	v_mfma_f32_32x32x16_bf16 v[128:143], v[66:69], v[176:179], v[128:143]
	v_exp_f32_e32 v100, v104
	v_exp_f32_e32 v101, v105
	v_exp_f32_e32 v102, v106
	v_exp_f32_e32 v103, v107
	s_waitcnt lgkmcnt(4)
	v_mfma_f32_32x32x16_bf16 v[112:127], v[74:77], v[176:179], v[112:127]
	v_exp_f32_e32 v104, v108
	v_exp_f32_e32 v105, v109
	v_exp_f32_e32 v106, v110
	v_exp_f32_e32 v107, v111
	s_waitcnt lgkmcnt(3)
	v_mfma_f32_32x32x16_bf16 v[128:143], v[144:147], v[172:175], v[128:143]
	v_exp_f32_e32 v108, v80
	v_exp_f32_e32 v109, v81
	v_exp_f32_e32 v110, v82
	v_exp_f32_e32 v111, v83
	s_waitcnt lgkmcnt(1)
	v_mfma_f32_32x32x16_bf16 v[112:127], v[160:163], v[172:175], v[112:127]
	v_exp_f32_e32 v144, v84
	v_exp_f32_e32 v145, v85
	v_exp_f32_e32 v146, v86
	v_exp_f32_e32 v147, v87
	v_mfma_f32_32x32x16_bf16 v[128:143], v[148:151], v[168:171], v[128:143]
	v_exp_f32_e32 v216, v88
	v_exp_f32_e32 v217, v89
	v_exp_f32_e32 v218, v90
	v_exp_f32_e32 v219, v91
	s_waitcnt lgkmcnt(0)
	v_mfma_f32_32x32x16_bf16 v[112:127], v[184:187], v[168:171], v[112:127]
	v_exp_f32_e32 v148, v92
	v_exp_f32_e32 v149, v93
	v_exp_f32_e32 v150, v94
	v_exp_f32_e32 v151, v95
	v_add_f32_e32 v1, v64, v1
	v_add_u32_e32 v92, s28, v195
	ds_read_b128 v[240:243], v195 offset:27648
	ds_read_b128 v[244:247], v195 offset:32256
	ds_read_b128 v[64:67], v92 offset:41472
	ds_read_b128 v[68:71], v92 offset:36864
	ds_read_b128 v[72:75], v92 offset:36896
	ds_read_b128 v[76:79], v92 offset:41504
	ds_read_b128 v[80:83], v92 offset:36928
	ds_read_b128 v[84:87], v92 offset:41536
	ds_read_b128 v[88:91], v92 offset:36960
	ds_read_b128 v[92:95], v92 offset:41568
	s_cmp_gt_i32 s27, 2
	s_cselect_b32 s29, -3, 2
	s_add_i32 s29, s29, s27
	s_add_i32 s28, s13, -6
	s_mulk_i32 s29, 0x2400
	s_min_u32 s28, s28, s12
	v_add_u32_e32 v10, s29, v208
	s_min_u32 s26, s26, s12
	s_lshl_b32 s92, s28, 13
	s_waitcnt vmcnt(3)
	ds_write_b128 v208, v[152:155]
	s_waitcnt vmcnt(2)
	ds_write_b128 v10, v[156:159] offset:36864
	s_add_u32 vcc_lo, s100, s92
	s_addc_u32 vcc_hi, s101, 0
	global_load_dwordx4 v[10:13], v248, vcc
	s_lshl_b32 s92, s26, 7
	s_add_u32 vcc_lo, s98, s92
	s_addc_u32 vcc_hi, s99, 0
	global_load_dwordx4 v[160:163], v249, vcc
	s_add_i32 s29, s27, 1
	s_setprio 1
	v_cvt_pk_bf16_f32 v96, v166, v167
	v_cvt_pk_bf16_f32 v97, v210, v211
	v_cvt_pk_bf16_f32 v98, v212, v213
	v_cvt_pk_bf16_f32 v99, v214, v215
	s_waitcnt lgkmcnt(8)
	s_nop 0
	v_mfma_f32_32x32x16_bf16 v[16:31], v[68:71], v[96:99], v[16:31]
	v_add_f32_e32 v184, v166, v167
	v_add_f32_e32 v184, v184, v210
	v_add_f32_e32 v184, v184, v211
	s_nop 0
	v_mfma_f32_32x32x16_bf16 v[32:47], v[64:67], v[96:99], v[32:47]
	v_cvt_pk_bf16_f32 v68, v100, v101
	v_cvt_pk_bf16_f32 v69, v102, v103
	v_cvt_pk_bf16_f32 v70, v104, v105
	v_cvt_pk_bf16_f32 v71, v106, v107
	v_add_f32_e32 v184, v184, v212
	v_add_f32_e32 v184, v184, v213
	v_add_f32_e32 v184, v184, v214
	v_add_f32_e32 v184, v184, v215
	s_waitcnt lgkmcnt(7)
	v_mfma_f32_32x32x16_bf16 v[16:31], v[72:75], v[68:71], v[16:31]
	v_add_f32_e32 v184, v184, v100
	v_add_f32_e32 v184, v184, v101
	v_add_f32_e32 v184, v184, v102
	v_add_f32_e32 v184, v184, v103
	s_waitcnt lgkmcnt(6)
	v_mfma_f32_32x32x16_bf16 v[32:47], v[76:79], v[68:71], v[32:47]
	v_cvt_pk_bf16_f32 v64, v108, v109
	v_cvt_pk_bf16_f32 v65, v110, v111
	v_cvt_pk_bf16_f32 v66, v144, v145
	v_cvt_pk_bf16_f32 v67, v146, v147
	v_add_f32_e32 v184, v184, v104
	v_add_f32_e32 v184, v184, v105
	v_add_f32_e32 v184, v184, v106
	v_add_f32_e32 v184, v184, v107
	s_waitcnt lgkmcnt(5)
	v_mfma_f32_32x32x16_bf16 v[16:31], v[80:83], v[64:67], v[16:31]
	v_add_f32_e32 v184, v184, v108
	v_add_f32_e32 v184, v184, v109
	v_add_f32_e32 v184, v184, v110
	v_add_f32_e32 v184, v184, v111
	s_waitcnt lgkmcnt(4)
	v_mfma_f32_32x32x16_bf16 v[32:47], v[84:87], v[64:67], v[32:47]
	v_cvt_pk_bf16_f32 v68, v216, v217
	v_cvt_pk_bf16_f32 v69, v218, v219
	v_cvt_pk_bf16_f32 v70, v148, v149
	v_cvt_pk_bf16_f32 v71, v150, v151
	v_add_f32_e32 v184, v184, v144
	v_add_f32_e32 v184, v184, v145
	v_add_f32_e32 v184, v184, v146
	v_add_f32_e32 v184, v184, v147
	s_waitcnt lgkmcnt(3)
	v_mfma_f32_32x32x16_bf16 v[16:31], v[88:91], v[68:71], v[16:31]
	v_add_f32_e32 v184, v184, v216
	v_add_f32_e32 v184, v184, v217
	v_add_f32_e32 v184, v184, v218
	v_add_f32_e32 v184, v184, v219
	s_waitcnt lgkmcnt(2)
	v_mfma_f32_32x32x16_bf16 v[32:47], v[92:95], v[68:71], v[32:47]
	v_add_f32_e32 v184, v184, v148
	v_add_f32_e32 v184, v184, v149
	v_add_f32_e32 v184, v184, v150
	v_add_f32_e32 v184, v184, v151
	s_setprio 0
	ds_read_b128 v[68:71], v195 offset:27680
	ds_read_b128 v[76:79], v195 offset:32288
	ds_read_b128 v[80:83], v195 offset:27712
	ds_read_b128 v[84:87], v195 offset:27744
	ds_read_b128 v[88:91], v195 offset:32320
	ds_read_b128 v[92:95], v195 offset:32352
	s_cmp_lg_u32 s27, 4
	s_cselect_b32 s26, s29, 0
	s_waitcnt lgkmcnt(6)
	v_mfma_f32_32x32x16_bf16 v[144:159], v[240:243], v[180:183], v[48:63]
	v_exp_f32_e32 v166, v128
	v_exp_f32_e32 v167, v129
	v_exp_f32_e32 v185, v130
	v_exp_f32_e32 v186, v131
	s_waitcnt lgkmcnt(5)
	v_mfma_f32_32x32x16_bf16 v[96:111], v[244:247], v[180:183], v[48:63]
	v_exp_f32_e32 v128, v132
	v_exp_f32_e32 v129, v133
	v_exp_f32_e32 v130, v134
	v_exp_f32_e32 v131, v135
	v_mfma_f32_32x32x16_bf16 v[144:159], v[68:71], v[176:179], v[144:159]
	v_exp_f32_e32 v132, v136
	v_exp_f32_e32 v133, v137
	v_exp_f32_e32 v134, v138
	v_exp_f32_e32 v135, v139
	s_waitcnt lgkmcnt(4)
	v_mfma_f32_32x32x16_bf16 v[96:111], v[76:79], v[176:179], v[96:111]
	v_exp_f32_e32 v136, v140
	v_exp_f32_e32 v137, v141
	v_exp_f32_e32 v138, v142
	v_exp_f32_e32 v139, v143
	s_waitcnt lgkmcnt(3)
	v_mfma_f32_32x32x16_bf16 v[144:159], v[80:83], v[172:175], v[144:159]
	v_exp_f32_e32 v140, v112
	v_exp_f32_e32 v141, v113
	v_exp_f32_e32 v142, v114
	v_exp_f32_e32 v143, v115
	s_waitcnt lgkmcnt(1)
	v_mfma_f32_32x32x16_bf16 v[96:111], v[88:91], v[172:175], v[96:111]
	v_exp_f32_e32 v187, v116
	v_exp_f32_e32 v210, v117
	v_exp_f32_e32 v211, v118
	v_exp_f32_e32 v212, v119
	v_mfma_f32_32x32x16_bf16 v[144:159], v[84:87], v[168:171], v[144:159]
	v_exp_f32_e32 v116, v120
	v_exp_f32_e32 v117, v121
	v_exp_f32_e32 v118, v122
	v_exp_f32_e32 v119, v123
	s_waitcnt lgkmcnt(0)
	v_mfma_f32_32x32x16_bf16 v[96:111], v[92:95], v[168:171], v[96:111]
	v_exp_f32_e32 v120, v124
	v_exp_f32_e32 v121, v125
	v_exp_f32_e32 v122, v126
	v_exp_f32_e32 v123, v127
	s_cmp_gt_i32 s26, 2
	s_cselect_b32 s27, -3, 2
	s_add_i32 s27, s27, s26
	s_mulk_i32 s27, 0x2400
	s_waitcnt vmcnt(3)
	ds_write_b128 v208, v[2:5] offset:9216
	v_add_u32_e32 v2, s27, v208
	s_add_i32 s27, s26, 1
	s_cmp_lg_u32 s26, 4
	s_cselect_b32 s26, s27, 0
	s_add_i32 s27, s13, -5
	s_min_u32 s27, s27, s12
	s_lshl_b32 s92, s27, 13
	s_waitcnt vmcnt(2)
	ds_write_b128 v2, v[6:9] offset:36864
	s_add_u32 vcc_lo, s100, s92
	s_addc_u32 vcc_hi, s101, 0
	global_load_dwordx4 v[6:9], v248, vcc
	s_lshl_b32 s92, s28, 7
	s_add_u32 vcc_lo, s98, s92
	s_addc_u32 vcc_hi, s99, 0
	global_load_dwordx4 v[2:5], v249, vcc
	s_nop 0
	s_mul_i32 s28, s26, 0x2400
	s_add_i32 s29, s28, 0xffffdc00
	s_cmp_lg_u32 s26, 0
	s_cselect_b32 s29, s29, 0x9000
	v_add_u32_e32 v92, s29, v195
	ds_read_b128 v[64:67], v92 offset:36864
	ds_read_b128 v[68:71], v92 offset:36896
	ds_read_b128 v[72:75], v92 offset:41472
	ds_read_b128 v[76:79], v92 offset:41504
	ds_read_b128 v[80:83], v92 offset:36928
	ds_read_b128 v[84:87], v92 offset:36960
	ds_read_b128 v[88:91], v92 offset:41536
	ds_read_b128 v[92:95], v92 offset:41568
	s_setprio 3
	v_cvt_pk_bf16_f32 v112, v166, v167
	v_cvt_pk_bf16_f32 v113, v185, v186
	v_cvt_pk_bf16_f32 v114, v128, v129
	v_cvt_pk_bf16_f32 v115, v130, v131
	s_waitcnt lgkmcnt(7)
	s_nop 0
	v_mfma_f32_32x32x16_bf16 v[16:31], v[64:67], v[112:115], v[16:31]
	v_add_f32_e32 v213, v166, v167
	v_add_f32_e32 v213, v213, v185
	v_add_f32_e32 v213, v213, v186
	s_waitcnt lgkmcnt(5)
	v_mfma_f32_32x32x16_bf16 v[32:47], v[72:75], v[112:115], v[32:47]
	v_cvt_pk_bf16_f32 v64, v132, v133
	v_cvt_pk_bf16_f32 v65, v134, v135
	v_cvt_pk_bf16_f32 v66, v136, v137
	v_cvt_pk_bf16_f32 v67, v138, v139
	v_add_f32_e32 v213, v213, v128
	v_add_f32_e32 v213, v213, v129
	v_add_f32_e32 v213, v213, v130
	v_add_f32_e32 v213, v213, v131
	s_nop 0
	v_mfma_f32_32x32x16_bf16 v[16:31], v[68:71], v[64:67], v[16:31]
	v_add_f32_e32 v213, v213, v132
	v_add_f32_e32 v213, v213, v133
	v_add_f32_e32 v213, v213, v134
	v_add_f32_e32 v213, v213, v135
	s_waitcnt lgkmcnt(4)
	v_mfma_f32_32x32x16_bf16 v[32:47], v[76:79], v[64:67], v[32:47]
	v_cvt_pk_bf16_f32 v68, v140, v141
	v_cvt_pk_bf16_f32 v69, v142, v143
	v_cvt_pk_bf16_f32 v70, v187, v210
	v_cvt_pk_bf16_f32 v71, v211, v212
	v_add_f32_e32 v213, v213, v136
	v_add_f32_e32 v213, v213, v137
	v_add_f32_e32 v213, v213, v138
	v_add_f32_e32 v213, v213, v139
	s_waitcnt lgkmcnt(3)
	v_mfma_f32_32x32x16_bf16 v[16:31], v[80:83], v[68:71], v[16:31]
	v_add_f32_e32 v213, v213, v140
	v_add_f32_e32 v213, v213, v141
	v_add_f32_e32 v213, v213, v142
	v_add_f32_e32 v213, v213, v143
	s_waitcnt lgkmcnt(1)
	v_mfma_f32_32x32x16_bf16 v[32:47], v[88:91], v[68:71], v[32:47]
	v_cvt_pk_bf16_f32 v64, v116, v117
	v_cvt_pk_bf16_f32 v65, v118, v119
	v_cvt_pk_bf16_f32 v66, v120, v121
	v_cvt_pk_bf16_f32 v67, v122, v123
	v_add_f32_e32 v213, v213, v187
	v_add_f32_e32 v213, v213, v210
	v_add_f32_e32 v213, v213, v211
	v_add_f32_e32 v213, v213, v212
	s_nop 0
	v_mfma_f32_32x32x16_bf16 v[16:31], v[84:87], v[64:67], v[16:31]
	v_add_f32_e32 v213, v213, v116
	v_add_f32_e32 v213, v213, v117
	v_add_f32_e32 v213, v213, v118
	v_add_f32_e32 v213, v213, v119
	s_waitcnt lgkmcnt(0)
	v_mfma_f32_32x32x16_bf16 v[32:47], v[92:95], v[64:67], v[32:47]
	v_add_f32_e32 v213, v213, v120
	v_add_f32_e32 v213, v213, v121
	v_add_f32_e32 v213, v213, v122
	v_add_f32_e32 v213, v213, v123
	s_setprio 2
	s_waitcnt lgkmcnt(0)
	s_barrier
	ds_read_b128 v[240:243], v195
	ds_read_b128 v[244:247], v195 offset:4608
	ds_read_b128 v[116:119], v195 offset:32
	ds_read_b128 v[120:123], v195 offset:4640
	ds_read_b128 v[124:127], v195 offset:64
	ds_read_b128 v[128:131], v195 offset:4672
	ds_read_b128 v[132:135], v195 offset:96
	ds_read_b128 v[136:139], v195 offset:4704
	v_add_f32_e32 v1, v1, v184
	v_exp_f32_e32 v140, v144
	v_exp_f32_e32 v141, v145
	v_exp_f32_e32 v142, v146
	v_exp_f32_e32 v143, v147
	v_exp_f32_e32 v144, v148
	v_exp_f32_e32 v145, v149
	v_exp_f32_e32 v146, v150
	v_exp_f32_e32 v147, v151
	s_waitcnt lgkmcnt(6)
	v_mfma_f32_32x32x16_bf16 v[80:95], v[240:243], v[180:183], v[48:63]
	v_mfma_f32_32x32x16_bf16 v[64:79], v[244:247], v[180:183], v[48:63]
	s_waitcnt lgkmcnt(5)
	v_mfma_f32_32x32x16_bf16 v[80:95], v[116:119], v[176:179], v[80:95]
	v_exp_f32_e32 v148, v152
	v_exp_f32_e32 v149, v153
	v_exp_f32_e32 v150, v154
	v_exp_f32_e32 v151, v155
	s_waitcnt lgkmcnt(4)
	v_mfma_f32_32x32x16_bf16 v[64:79], v[120:123], v[176:179], v[64:79]
	v_exp_f32_e32 v152, v156
	v_exp_f32_e32 v153, v157
	v_exp_f32_e32 v154, v158
	v_exp_f32_e32 v155, v159
	s_waitcnt lgkmcnt(3)
	v_mfma_f32_32x32x16_bf16 v[80:95], v[124:127], v[172:175], v[80:95]
	v_exp_f32_e32 v156, v96
	v_exp_f32_e32 v157, v97
	v_exp_f32_e32 v158, v98
	v_exp_f32_e32 v159, v99
	s_waitcnt lgkmcnt(2)
	v_mfma_f32_32x32x16_bf16 v[64:79], v[128:131], v[172:175], v[64:79]
	v_exp_f32_e32 v166, v100
	v_exp_f32_e32 v167, v101
	v_exp_f32_e32 v184, v102
	v_exp_f32_e32 v185, v103
	s_waitcnt lgkmcnt(1)
	v_mfma_f32_32x32x16_bf16 v[80:95], v[132:135], v[168:171], v[80:95]
	v_exp_f32_e32 v186, v104
	v_exp_f32_e32 v187, v105
	v_exp_f32_e32 v210, v106
	v_exp_f32_e32 v211, v107
	s_waitcnt lgkmcnt(0)
	v_mfma_f32_32x32x16_bf16 v[64:79], v[136:139], v[168:171], v[64:79]
	v_exp_f32_e32 v212, v108
	v_exp_f32_e32 v214, v109
	v_exp_f32_e32 v215, v110
	v_exp_f32_e32 v216, v111
	v_add_u32_e32 v124, s28, v195
	ds_read_b128 v[240:243], v195 offset:9216
	ds_read_b128 v[244:247], v195 offset:13824
	ds_read_b128 v[96:99], v124 offset:41472
	ds_read_b128 v[100:103], v124 offset:36864
	ds_read_b128 v[104:107], v124 offset:36896
	ds_read_b128 v[108:111], v124 offset:41504
	ds_read_b128 v[112:115], v124 offset:36928
	ds_read_b128 v[116:119], v124 offset:41536
	ds_read_b128 v[120:123], v124 offset:36960
	ds_read_b128 v[124:127], v124 offset:41568
	s_cmp_gt_i32 s26, 2
	s_cselect_b32 s29, -3, 2
	s_add_i32 s29, s29, s26
	s_mulk_i32 s29, 0x2400
	s_waitcnt vmcnt(3)
	ds_write_b128 v208, v[10:13] offset:18432
	v_add_u32_e32 v10, s29, v208
	s_mov_b32 s29, 0x1da90000
	s_waitcnt vmcnt(2)
	ds_write_b128 v10, v[160:163] offset:36864
	s_add_i32 s92, s13, -4
	s_lshl_b32 s92, s92, 13
	s_add_u32 vcc_lo, s100, s92
	s_addc_u32 vcc_hi, s101, 0
	global_load_dwordx4 v[128:131], v248, vcc
	s_lshl_b32 s92, s27, 7
	s_add_u32 vcc_lo, s98, s92
	s_addc_u32 vcc_hi, s99, 0
	global_load_dwordx4 v[10:13], v249, vcc
	v_add_f32_e32 v1, v1, v213
	s_add_i32 s28, s26, 1
	s_setprio 1
	v_cvt_pk_bf16_f32 v132, v140, v141
	v_cvt_pk_bf16_f32 v133, v142, v143
	v_cvt_pk_bf16_f32 v134, v144, v145
	v_cvt_pk_bf16_f32 v135, v146, v147
	s_waitcnt lgkmcnt(8)
	s_nop 0
	v_mfma_f32_32x32x16_bf16 v[16:31], v[100:103], v[132:135], v[16:31]
	v_add_f32_e32 v160, v140, v141
	v_add_f32_e32 v160, v160, v142
	v_add_f32_e32 v160, v160, v143
	s_nop 0
	v_mfma_f32_32x32x16_bf16 v[32:47], v[96:99], v[132:135], v[32:47]
	v_cvt_pk_bf16_f32 v100, v148, v149
	v_cvt_pk_bf16_f32 v101, v150, v151
	v_cvt_pk_bf16_f32 v102, v152, v153
	v_cvt_pk_bf16_f32 v103, v154, v155
	v_add_f32_e32 v160, v160, v144
	v_add_f32_e32 v160, v160, v145
	v_add_f32_e32 v160, v160, v146
	v_add_f32_e32 v160, v160, v147
	s_waitcnt lgkmcnt(7)
	v_mfma_f32_32x32x16_bf16 v[16:31], v[104:107], v[100:103], v[16:31]
	v_add_f32_e32 v160, v160, v148
	v_add_f32_e32 v160, v160, v149
	v_add_f32_e32 v160, v160, v150
	v_add_f32_e32 v160, v160, v151
	s_waitcnt lgkmcnt(6)
	v_mfma_f32_32x32x16_bf16 v[32:47], v[108:111], v[100:103], v[32:47]
	v_cvt_pk_bf16_f32 v96, v156, v157
	v_cvt_pk_bf16_f32 v97, v158, v159
	v_cvt_pk_bf16_f32 v98, v166, v167
	v_cvt_pk_bf16_f32 v99, v184, v185
	v_add_f32_e32 v160, v160, v152
	v_add_f32_e32 v160, v160, v153
	v_add_f32_e32 v160, v160, v154
	v_add_f32_e32 v160, v160, v155
	s_waitcnt lgkmcnt(5)
	v_mfma_f32_32x32x16_bf16 v[16:31], v[112:115], v[96:99], v[16:31]
	v_add_f32_e32 v160, v160, v156
	v_add_f32_e32 v160, v160, v157
	v_add_f32_e32 v160, v160, v158
	v_add_f32_e32 v160, v160, v159
	s_waitcnt lgkmcnt(4)
	v_mfma_f32_32x32x16_bf16 v[32:47], v[116:119], v[96:99], v[32:47]
	v_cvt_pk_bf16_f32 v100, v186, v187
	v_cvt_pk_bf16_f32 v101, v210, v211
	v_cvt_pk_bf16_f32 v102, v212, v214
	v_cvt_pk_bf16_f32 v103, v215, v216
	v_add_f32_e32 v160, v160, v166
	v_add_f32_e32 v160, v160, v167
	v_add_f32_e32 v160, v160, v184
	v_add_f32_e32 v160, v160, v185
	s_waitcnt lgkmcnt(3)
	v_mfma_f32_32x32x16_bf16 v[16:31], v[120:123], v[100:103], v[16:31]
	v_add_f32_e32 v160, v160, v186
	v_add_f32_e32 v160, v160, v187
	v_add_f32_e32 v160, v160, v210
	v_add_f32_e32 v160, v160, v211
	s_waitcnt lgkmcnt(2)
	v_mfma_f32_32x32x16_bf16 v[32:47], v[124:127], v[100:103], v[32:47]
	v_add_f32_e32 v160, v160, v212
	v_add_f32_e32 v160, v160, v214
	v_add_f32_e32 v160, v160, v215
	v_add_f32_e32 v160, v160, v216
	s_setprio 0
	ds_read_b128 v[132:135], v195 offset:9248
	ds_read_b128 v[140:143], v195 offset:13856
	ds_read_b128 v[144:147], v195 offset:9280
	ds_read_b128 v[148:151], v195 offset:9312
	ds_read_b128 v[152:155], v195 offset:13888
	ds_read_b128 v[156:159], v195 offset:13920
	s_cmp_lg_u32 s26, 4
	s_cselect_b32 s26, s28, 0
	s_waitcnt lgkmcnt(6)
	v_mfma_f32_32x32x16_bf16 v[112:127], v[240:243], v[180:183], v[48:63]
	v_exp_f32_e32 v161, v80
	v_exp_f32_e32 v162, v81
	v_exp_f32_e32 v163, v82
	v_exp_f32_e32 v164, v83
	s_waitcnt lgkmcnt(5)
	v_mfma_f32_32x32x16_bf16 v[96:111], v[244:247], v[180:183], v[48:63]
	v_exp_f32_e32 v165, v84
	v_exp_f32_e32 v166, v85
	v_exp_f32_e32 v167, v86
	v_exp_f32_e32 v184, v87
	v_mfma_f32_32x32x16_bf16 v[112:127], v[132:135], v[176:179], v[112:127]
	v_exp_f32_e32 v136, v88
	v_exp_f32_e32 v137, v89
	v_exp_f32_e32 v138, v90
	v_exp_f32_e32 v139, v91
	s_waitcnt lgkmcnt(4)
	v_mfma_f32_32x32x16_bf16 v[96:111], v[140:143], v[176:179], v[96:111]
	v_exp_f32_e32 v185, v92
	v_exp_f32_e32 v186, v93
	v_exp_f32_e32 v187, v94
	v_exp_f32_e32 v210, v95
	s_waitcnt lgkmcnt(3)
	v_mfma_f32_32x32x16_bf16 v[112:127], v[144:147], v[172:175], v[112:127]
	v_exp_f32_e32 v140, v64
	v_exp_f32_e32 v141, v65
	v_exp_f32_e32 v142, v66
	v_exp_f32_e32 v143, v67
	s_waitcnt lgkmcnt(1)
	v_mfma_f32_32x32x16_bf16 v[96:111], v[152:155], v[172:175], v[96:111]
	v_exp_f32_e32 v144, v68
	v_exp_f32_e32 v145, v69
	v_exp_f32_e32 v146, v70
	v_exp_f32_e32 v147, v71
	v_mfma_f32_32x32x16_bf16 v[112:127], v[148:151], v[168:171], v[112:127]
	v_exp_f32_e32 v152, v72
	v_exp_f32_e32 v153, v73
	v_exp_f32_e32 v154, v74
	v_exp_f32_e32 v155, v75
	s_waitcnt lgkmcnt(0)
	v_mfma_f32_32x32x16_bf16 v[96:111], v[156:159], v[168:171], v[96:111]
	v_exp_f32_e32 v148, v76
	v_exp_f32_e32 v149, v77
	v_exp_f32_e32 v150, v78
	v_exp_f32_e32 v151, v79
	s_cmp_gt_i32 s26, 2
	s_cselect_b32 s27, -3, 2
	s_add_i32 s27, s27, s26
	s_mulk_i32 s27, 0x2400
	s_waitcnt vmcnt(3)
	ds_write_b128 v208, v[6:9] offset:27648
	v_add_u32_e32 v6, s27, v208
	s_add_i32 s27, s26, 1
	s_cmp_lg_u32 s26, 4
	s_cselect_b32 s27, s27, 0
	s_add_i32 s26, s13, -3
	s_min_u32 s28, s26, s12
	s_lshl_b32 s92, s28, 13
	s_waitcnt vmcnt(2)
	ds_write_b128 v6, v[2:5] offset:36864
	s_add_u32 vcc_lo, s100, s92
	s_addc_u32 vcc_hi, s101, 0
	global_load_dwordx4 v[6:9], v248, vcc
	s_nop 0
	s_add_i32 s92, s13, -4
	s_lshl_b32 s92, s92, 7
	s_add_u32 vcc_lo, s98, s92
	s_addc_u32 vcc_hi, s99, 0
	global_load_dwordx4 v[2:5], v249, vcc
	s_mul_i32 s29, s27, 0x2400
	s_add_i32 s34, s29, 0xffffdc00
	s_cmp_lg_u32 s27, 0
	s_cselect_b32 s34, s34, 0x9000
	v_add_u32_e32 v14, s34, v195
	ds_read_b128 v[64:67], v14 offset:36864
	ds_read_b128 v[68:71], v14 offset:36896
	ds_read_b128 v[72:75], v14 offset:41472
	ds_read_b128 v[76:79], v14 offset:41504
	ds_read_b128 v[80:83], v14 offset:36928
	ds_read_b128 v[84:87], v14 offset:36960
	ds_read_b128 v[88:91], v14 offset:41536
	ds_read_b128 v[92:95], v14 offset:41568
	s_setprio 3
	v_cvt_pk_bf16_f32 v132, v161, v162
	v_cvt_pk_bf16_f32 v133, v163, v164
	v_cvt_pk_bf16_f32 v134, v165, v166
	v_cvt_pk_bf16_f32 v135, v167, v184
	s_waitcnt lgkmcnt(7)
	s_nop 0
	v_mfma_f32_32x32x16_bf16 v[16:31], v[64:67], v[132:135], v[16:31]
	v_add_f32_e32 v14, v161, v162
	v_add_f32_e32 v14, v14, v163
	v_add_f32_e32 v14, v14, v164
	s_waitcnt lgkmcnt(5)
	v_mfma_f32_32x32x16_bf16 v[32:47], v[72:75], v[132:135], v[32:47]
	v_cvt_pk_bf16_f32 v64, v136, v137
	v_cvt_pk_bf16_f32 v65, v138, v139
	v_cvt_pk_bf16_f32 v66, v185, v186
	v_cvt_pk_bf16_f32 v67, v187, v210
	v_add_f32_e32 v14, v14, v165
	v_add_f32_e32 v14, v14, v166
	v_add_f32_e32 v14, v14, v167
	v_add_f32_e32 v14, v14, v184
	s_nop 0
	v_mfma_f32_32x32x16_bf16 v[16:31], v[68:71], v[64:67], v[16:31]
	v_add_f32_e32 v14, v14, v136
	v_add_f32_e32 v14, v14, v137
	v_add_f32_e32 v14, v14, v138
	v_add_f32_e32 v14, v14, v139
	s_waitcnt lgkmcnt(4)
	v_mfma_f32_32x32x16_bf16 v[32:47], v[76:79], v[64:67], v[32:47]
	v_cvt_pk_bf16_f32 v68, v140, v141
	v_cvt_pk_bf16_f32 v69, v142, v143
	v_cvt_pk_bf16_f32 v70, v144, v145
	v_cvt_pk_bf16_f32 v71, v146, v147
	v_add_f32_e32 v14, v14, v185
	v_add_f32_e32 v14, v14, v186
	v_add_f32_e32 v14, v14, v187
	v_add_f32_e32 v14, v14, v210
	s_waitcnt lgkmcnt(3)
	v_mfma_f32_32x32x16_bf16 v[16:31], v[80:83], v[68:71], v[16:31]
	v_add_f32_e32 v14, v14, v140
	v_add_f32_e32 v14, v14, v141
	v_add_f32_e32 v14, v14, v142
	v_add_f32_e32 v14, v14, v143
	s_waitcnt lgkmcnt(1)
	v_mfma_f32_32x32x16_bf16 v[32:47], v[88:91], v[68:71], v[32:47]
	v_cvt_pk_bf16_f32 v64, v152, v153
	v_cvt_pk_bf16_f32 v65, v154, v155
	v_cvt_pk_bf16_f32 v66, v148, v149
	v_cvt_pk_bf16_f32 v67, v150, v151
	v_add_f32_e32 v14, v14, v144
	v_add_f32_e32 v14, v14, v145
	v_add_f32_e32 v14, v14, v146
	v_add_f32_e32 v14, v14, v147
	s_nop 0
	v_mfma_f32_32x32x16_bf16 v[16:31], v[84:87], v[64:67], v[16:31]
	v_add_f32_e32 v14, v14, v152
	v_add_f32_e32 v14, v14, v153
	v_add_f32_e32 v14, v14, v154
	v_add_f32_e32 v14, v14, v155
	s_waitcnt lgkmcnt(0)
	v_mfma_f32_32x32x16_bf16 v[32:47], v[92:95], v[64:67], v[32:47]
	v_add_f32_e32 v14, v14, v148
	v_add_f32_e32 v14, v14, v149
	v_add_f32_e32 v14, v14, v150
	v_add_f32_e32 v14, v14, v151
	s_setprio 2
	s_waitcnt lgkmcnt(0)
	s_barrier
	ds_read_b128 v[240:243], v195 offset:18432
	ds_read_b128 v[244:247], v195 offset:23040
	ds_read_b128 v[136:139], v195 offset:18464
	ds_read_b128 v[140:143], v195 offset:23072
	ds_read_b128 v[144:147], v195 offset:18496
	ds_read_b128 v[148:151], v195 offset:23104
	ds_read_b128 v[152:155], v195 offset:18528
	ds_read_b128 v[156:159], v195 offset:23136
	v_add_f32_e32 v1, v1, v160
	v_exp_f32_e32 v160, v112
	v_exp_f32_e32 v161, v113
	v_exp_f32_e32 v162, v114
	v_exp_f32_e32 v163, v115
	v_exp_f32_e32 v164, v116
	v_exp_f32_e32 v165, v117
	v_exp_f32_e32 v166, v118
	v_exp_f32_e32 v167, v119
	s_waitcnt lgkmcnt(6)
	v_mfma_f32_32x32x16_bf16 v[80:95], v[240:243], v[180:183], v[48:63]
	v_mfma_f32_32x32x16_bf16 v[64:79], v[244:247], v[180:183], v[48:63]
	s_waitcnt lgkmcnt(5)
	v_mfma_f32_32x32x16_bf16 v[80:95], v[136:139], v[176:179], v[80:95]
	v_exp_f32_e32 v184, v120
	v_exp_f32_e32 v185, v121
	v_exp_f32_e32 v186, v122
	v_exp_f32_e32 v187, v123
	s_waitcnt lgkmcnt(4)
	v_mfma_f32_32x32x16_bf16 v[64:79], v[140:143], v[176:179], v[64:79]
	v_exp_f32_e32 v136, v124
	v_exp_f32_e32 v137, v125
	v_exp_f32_e32 v138, v126
	v_exp_f32_e32 v139, v127
	s_waitcnt lgkmcnt(3)
	v_mfma_f32_32x32x16_bf16 v[80:95], v[144:147], v[172:175], v[80:95]
	v_exp_f32_e32 v140, v96
	v_exp_f32_e32 v141, v97
	v_exp_f32_e32 v142, v98
	v_exp_f32_e32 v143, v99
	s_waitcnt lgkmcnt(2)
	v_mfma_f32_32x32x16_bf16 v[64:79], v[148:151], v[172:175], v[64:79]
	v_exp_f32_e32 v144, v100
	v_exp_f32_e32 v145, v101
	v_exp_f32_e32 v146, v102
	v_exp_f32_e32 v147, v103
	s_waitcnt lgkmcnt(1)
	v_mfma_f32_32x32x16_bf16 v[80:95], v[152:155], v[168:171], v[80:95]
	v_exp_f32_e32 v148, v104
	v_exp_f32_e32 v149, v105
	v_exp_f32_e32 v150, v106
	v_exp_f32_e32 v151, v107
	s_waitcnt lgkmcnt(0)
	v_mfma_f32_32x32x16_bf16 v[64:79], v[156:159], v[168:171], v[64:79]
	v_exp_f32_e32 v152, v108
	v_exp_f32_e32 v153, v109
	v_exp_f32_e32 v154, v110
	v_exp_f32_e32 v155, v111
	s_cmp_gt_i32 s27, 2
	s_cselect_b32 s34, -3, 2
	s_waitcnt vmcnt(3)
	ds_write_b128 v208, v[128:131]
	v_add_u32_e32 v128, s29, v195
	ds_read_b128 v[240:243], v195 offset:27648
	ds_read_b128 v[244:247], v195 offset:32256
	ds_read_b128 v[96:99], v128 offset:41472
	ds_read_b128 v[100:103], v128 offset:36864
	ds_read_b128 v[104:107], v128 offset:36896
	ds_read_b128 v[108:111], v128 offset:41504
	ds_read_b128 v[116:119], v128 offset:36928
	ds_read_b128 v[120:123], v128 offset:41536
	ds_read_b128 v[124:127], v128 offset:36960
	ds_read_b128 v[128:131], v128 offset:41568
	s_add_i32 s34, s34, s27
	s_add_i32 s29, s13, -2
	s_mulk_i32 s34, 0x2400
	s_min_u32 s29, s29, s12
	v_add_u32_e32 v15, s34, v208
	s_lshl_b32 s92, s29, 13
	s_waitcnt vmcnt(2)
	ds_write_b128 v15, v[10:13] offset:36864
	s_add_u32 vcc_lo, s100, s92
	s_addc_u32 vcc_hi, s101, 0
	global_load_dwordx4 v[10:13], v248, vcc
	s_lshl_b32 s92, s28, 7
	v_add_f32_e32 v1, v1, v14
	s_add_u32 vcc_lo, s98, s92
	s_addc_u32 vcc_hi, s99, 0
	global_load_dwordx4 v[112:115], v249, vcc
	s_add_i32 s34, s27, 1
	s_setprio 1
	v_cvt_pk_bf16_f32 v132, v160, v161
	v_cvt_pk_bf16_f32 v133, v162, v163
	v_cvt_pk_bf16_f32 v134, v164, v165
	v_cvt_pk_bf16_f32 v135, v166, v167
	s_waitcnt lgkmcnt(7)
	s_nop 0
	v_mfma_f32_32x32x16_bf16 v[16:31], v[100:103], v[132:135], v[16:31]
	v_add_f32_e32 v14, v160, v161
	v_add_f32_e32 v14, v14, v162
	v_add_f32_e32 v14, v14, v163
	s_nop 0
	v_mfma_f32_32x32x16_bf16 v[32:47], v[96:99], v[132:135], v[32:47]
	v_cvt_pk_bf16_f32 v100, v184, v185
	v_cvt_pk_bf16_f32 v101, v186, v187
	v_cvt_pk_bf16_f32 v102, v136, v137
	v_cvt_pk_bf16_f32 v103, v138, v139
	v_add_f32_e32 v14, v14, v164
	v_add_f32_e32 v14, v14, v165
	v_add_f32_e32 v14, v14, v166
	v_add_f32_e32 v14, v14, v167
	s_waitcnt lgkmcnt(6)
	v_mfma_f32_32x32x16_bf16 v[16:31], v[104:107], v[100:103], v[16:31]
	v_add_f32_e32 v14, v14, v184
	v_add_f32_e32 v14, v14, v185
	v_add_f32_e32 v14, v14, v186
	v_add_f32_e32 v14, v14, v187
	s_waitcnt lgkmcnt(5)
	v_mfma_f32_32x32x16_bf16 v[32:47], v[108:111], v[100:103], v[32:47]
	v_cvt_pk_bf16_f32 v96, v140, v141
	v_cvt_pk_bf16_f32 v97, v142, v143
	v_cvt_pk_bf16_f32 v98, v144, v145
	v_cvt_pk_bf16_f32 v99, v146, v147
	v_add_f32_e32 v14, v14, v136
	v_add_f32_e32 v14, v14, v137
	v_add_f32_e32 v14, v14, v138
	v_add_f32_e32 v14, v14, v139
	s_waitcnt lgkmcnt(4)
	v_mfma_f32_32x32x16_bf16 v[16:31], v[116:119], v[96:99], v[16:31]
	v_add_f32_e32 v14, v14, v140
	v_add_f32_e32 v14, v14, v141
	v_add_f32_e32 v14, v14, v142
	v_add_f32_e32 v14, v14, v143
	s_waitcnt lgkmcnt(3)
	v_mfma_f32_32x32x16_bf16 v[32:47], v[120:123], v[96:99], v[32:47]
	v_cvt_pk_bf16_f32 v100, v148, v149
	v_cvt_pk_bf16_f32 v101, v150, v151
	v_cvt_pk_bf16_f32 v102, v152, v153
	v_cvt_pk_bf16_f32 v103, v154, v155
	v_add_f32_e32 v14, v14, v144
	v_add_f32_e32 v14, v14, v145
	v_add_f32_e32 v14, v14, v146
	v_add_f32_e32 v14, v14, v147
	s_waitcnt lgkmcnt(2)
	v_mfma_f32_32x32x16_bf16 v[16:31], v[124:127], v[100:103], v[16:31]
	v_add_f32_e32 v14, v14, v148
	v_add_f32_e32 v14, v14, v149
	v_add_f32_e32 v14, v14, v150
	v_add_f32_e32 v14, v14, v151
	s_waitcnt lgkmcnt(1)
	v_mfma_f32_32x32x16_bf16 v[32:47], v[128:131], v[100:103], v[32:47]
	v_add_f32_e32 v14, v14, v152
	v_add_f32_e32 v14, v14, v153
	v_add_f32_e32 v14, v14, v154
	v_add_f32_e32 v14, v14, v155
	s_setprio 0
	ds_read_b128 v[116:119], v195 offset:27680
	ds_read_b128 v[124:127], v195 offset:32288
	ds_read_b128 v[128:131], v195 offset:27712
	ds_read_b128 v[132:135], v195 offset:27744
	ds_read_b128 v[136:139], v195 offset:32320
	ds_read_b128 v[140:143], v195 offset:32352
	s_cmp_lg_u32 s27, 4
	s_cselect_b32 s27, s34, 0
	s_waitcnt lgkmcnt(6)
	v_mfma_f32_32x32x16_bf16 v[152:167], v[240:243], v[180:183], v[48:63]
	v_exp_f32_e32 v15, v80
	v_exp_f32_e32 v144, v81
	v_exp_f32_e32 v145, v82
	v_exp_f32_e32 v146, v83
	s_waitcnt lgkmcnt(5)
	v_mfma_f32_32x32x16_bf16 v[96:111], v[244:247], v[180:183], v[48:63]
	v_exp_f32_e32 v147, v84
	v_exp_f32_e32 v148, v85
	v_exp_f32_e32 v149, v86
	v_exp_f32_e32 v150, v87
	v_mfma_f32_32x32x16_bf16 v[152:167], v[116:119], v[176:179], v[152:167]
	v_exp_f32_e32 v120, v88
	v_exp_f32_e32 v121, v89
	v_exp_f32_e32 v122, v90
	v_exp_f32_e32 v123, v91
	s_waitcnt lgkmcnt(4)
	v_mfma_f32_32x32x16_bf16 v[96:111], v[124:127], v[176:179], v[96:111]
	v_exp_f32_e32 v151, v92
	v_exp_f32_e32 v184, v93
	v_exp_f32_e32 v185, v94
	v_exp_f32_e32 v186, v95
	s_waitcnt lgkmcnt(3)
	v_mfma_f32_32x32x16_bf16 v[152:167], v[128:131], v[172:175], v[152:167]
	v_exp_f32_e32 v124, v64
	v_exp_f32_e32 v125, v65
	v_exp_f32_e32 v126, v66
	v_exp_f32_e32 v127, v67
	s_waitcnt lgkmcnt(1)
	v_mfma_f32_32x32x16_bf16 v[96:111], v[136:139], v[172:175], v[96:111]
	v_exp_f32_e32 v128, v68
	v_exp_f32_e32 v129, v69
	v_exp_f32_e32 v130, v70
	v_exp_f32_e32 v131, v71
	v_mfma_f32_32x32x16_bf16 v[152:167], v[132:135], v[168:171], v[152:167]
	v_exp_f32_e32 v136, v72
	v_exp_f32_e32 v137, v73
	v_exp_f32_e32 v138, v74
	v_exp_f32_e32 v139, v75
	s_waitcnt lgkmcnt(0)
	v_mfma_f32_32x32x16_bf16 v[96:111], v[140:143], v[168:171], v[96:111]
	v_exp_f32_e32 v132, v76
	v_exp_f32_e32 v133, v77
	v_exp_f32_e32 v134, v78
	v_exp_f32_e32 v135, v79
	s_cmp_gt_i32 s27, 2
	s_cselect_b32 s28, -3, 2
	s_add_i32 s28, s28, s27
	s_mulk_i32 s28, 0x2400
	s_waitcnt vmcnt(3)
	ds_write_b128 v208, v[6:9] offset:9216
	v_add_u32_e32 v6, s28, v208
	s_add_i32 s28, s27, 1
	s_cmp_lg_u32 s27, 4
	s_cselect_b32 s27, s28, 0
	s_add_i32 s28, s13, -1
	s_min_u32 s28, s28, s12
	s_lshl_b32 s92, s28, 13
	s_waitcnt vmcnt(2)
	ds_write_b128 v6, v[2:5] offset:36864
	s_add_u32 vcc_lo, s100, s92
	s_addc_u32 vcc_hi, s101, 0
	global_load_dwordx4 v[6:9], v248, vcc
	s_lshl_b32 s92, s29, 7
	s_add_u32 vcc_lo, s98, s92
	s_addc_u32 vcc_hi, s99, 0
	global_load_dwordx4 v[2:5], v249, vcc
	s_nop 0
	s_mul_i32 s29, s27, 0x2400
	s_add_i32 s34, s29, 0xffffdc00
	s_cmp_lg_u32 s27, 0
	s_cselect_b32 s34, s34, 0x9000
	v_add_u32_e32 v92, s34, v195
	ds_read_b128 v[64:67], v92 offset:36864
	ds_read_b128 v[68:71], v92 offset:36896
	ds_read_b128 v[72:75], v92 offset:41472
	ds_read_b128 v[76:79], v92 offset:41504
	ds_read_b128 v[80:83], v92 offset:36928
	ds_read_b128 v[84:87], v92 offset:36960
	ds_read_b128 v[88:91], v92 offset:41536
	ds_read_b128 v[92:95], v92 offset:41568
	s_setprio 3
	v_cvt_pk_bf16_f32 v116, v15, v144
	v_cvt_pk_bf16_f32 v117, v145, v146
	v_cvt_pk_bf16_f32 v118, v147, v148
	v_cvt_pk_bf16_f32 v119, v149, v150
	s_waitcnt lgkmcnt(7)
	s_nop 0
	v_mfma_f32_32x32x16_bf16 v[16:31], v[64:67], v[116:119], v[16:31]
	v_add_f32_e32 v187, v15, v144
	v_add_f32_e32 v187, v187, v145
	v_add_f32_e32 v187, v187, v146
	s_waitcnt lgkmcnt(5)
	v_mfma_f32_32x32x16_bf16 v[32:47], v[72:75], v[116:119], v[32:47]
	v_cvt_pk_bf16_f32 v64, v120, v121
	v_cvt_pk_bf16_f32 v65, v122, v123
	v_cvt_pk_bf16_f32 v66, v151, v184
	v_cvt_pk_bf16_f32 v67, v185, v186
	v_add_f32_e32 v187, v187, v147
	v_add_f32_e32 v187, v187, v148
	v_add_f32_e32 v187, v187, v149
	v_add_f32_e32 v187, v187, v150
	s_nop 0
	v_mfma_f32_32x32x16_bf16 v[16:31], v[68:71], v[64:67], v[16:31]
	v_add_f32_e32 v187, v187, v120
	v_add_f32_e32 v187, v187, v121
	v_add_f32_e32 v187, v187, v122
	v_add_f32_e32 v187, v187, v123
	s_waitcnt lgkmcnt(4)
	v_mfma_f32_32x32x16_bf16 v[32:47], v[76:79], v[64:67], v[32:47]
	v_cvt_pk_bf16_f32 v68, v124, v125
	v_cvt_pk_bf16_f32 v69, v126, v127
	v_cvt_pk_bf16_f32 v70, v128, v129
	v_cvt_pk_bf16_f32 v71, v130, v131
	v_add_f32_e32 v187, v187, v151
	v_add_f32_e32 v187, v187, v184
	v_add_f32_e32 v187, v187, v185
	v_add_f32_e32 v187, v187, v186
	s_waitcnt lgkmcnt(3)
	v_mfma_f32_32x32x16_bf16 v[16:31], v[80:83], v[68:71], v[16:31]
	v_add_f32_e32 v187, v187, v124
	v_add_f32_e32 v187, v187, v125
	v_add_f32_e32 v187, v187, v126
	v_add_f32_e32 v187, v187, v127
	s_waitcnt lgkmcnt(1)
	v_mfma_f32_32x32x16_bf16 v[32:47], v[88:91], v[68:71], v[32:47]
	v_cvt_pk_bf16_f32 v64, v136, v137
	v_cvt_pk_bf16_f32 v65, v138, v139
	v_cvt_pk_bf16_f32 v66, v132, v133
	v_cvt_pk_bf16_f32 v67, v134, v135
	v_add_f32_e32 v187, v187, v128
	v_add_f32_e32 v187, v187, v129
	v_add_f32_e32 v187, v187, v130
	v_add_f32_e32 v187, v187, v131
	s_nop 0
	v_mfma_f32_32x32x16_bf16 v[16:31], v[84:87], v[64:67], v[16:31]
	v_add_f32_e32 v187, v187, v136
	v_add_f32_e32 v187, v187, v137
	v_add_f32_e32 v187, v187, v138
	v_add_f32_e32 v187, v187, v139
	s_waitcnt lgkmcnt(0)
	v_mfma_f32_32x32x16_bf16 v[32:47], v[92:95], v[64:67], v[32:47]
	v_add_f32_e32 v187, v187, v132
	v_add_f32_e32 v187, v187, v133
	v_add_f32_e32 v187, v187, v134
	v_add_f32_e32 v187, v187, v135
	s_setprio 2
	s_waitcnt lgkmcnt(0)
	s_barrier
	ds_read_b128 v[240:243], v195
	ds_read_b128 v[244:247], v195 offset:4608
	ds_read_b128 v[72:75], v195 offset:32
	ds_read_b128 v[76:79], v195 offset:4640
	ds_read_b128 v[80:83], v195 offset:64
	ds_read_b128 v[84:87], v195 offset:4672
	ds_read_b128 v[88:91], v195 offset:96
	ds_read_b128 v[92:95], v195 offset:4704
	v_add_f32_e32 v1, v1, v14
	v_exp_f32_e32 v14, v152
	v_exp_f32_e32 v15, v153
	v_exp_f32_e32 v116, v154
	v_exp_f32_e32 v117, v155
	v_exp_f32_e32 v118, v156
	v_exp_f32_e32 v119, v157
	v_exp_f32_e32 v184, v158
	v_exp_f32_e32 v185, v159
	s_waitcnt lgkmcnt(6)
	v_mfma_f32_32x32x16_bf16 v[136:151], v[240:243], v[180:183], v[48:63]
	v_mfma_f32_32x32x16_bf16 v[120:135], v[244:247], v[180:183], v[48:63]
	s_waitcnt lgkmcnt(5)
	v_mfma_f32_32x32x16_bf16 v[136:151], v[72:75], v[176:179], v[136:151]
	v_exp_f32_e32 v186, v160
	v_exp_f32_e32 v210, v161
	v_exp_f32_e32 v211, v162
	v_exp_f32_e32 v212, v163
	s_waitcnt lgkmcnt(4)
	v_mfma_f32_32x32x16_bf16 v[120:135], v[76:79], v[176:179], v[120:135]
	v_exp_f32_e32 v160, v164
	v_exp_f32_e32 v161, v165
	v_exp_f32_e32 v162, v166
	v_exp_f32_e32 v163, v167
	s_waitcnt lgkmcnt(3)
	v_mfma_f32_32x32x16_bf16 v[136:151], v[80:83], v[172:175], v[136:151]
	v_exp_f32_e32 v164, v96
	v_exp_f32_e32 v165, v97
	v_exp_f32_e32 v166, v98
	v_exp_f32_e32 v167, v99
	s_waitcnt lgkmcnt(2)
	v_mfma_f32_32x32x16_bf16 v[120:135], v[84:87], v[172:175], v[120:135]
	v_exp_f32_e32 v96, v100
	v_exp_f32_e32 v97, v101
	v_exp_f32_e32 v98, v102
	v_exp_f32_e32 v99, v103
	s_waitcnt lgkmcnt(1)
	v_mfma_f32_32x32x16_bf16 v[136:151], v[88:91], v[168:171], v[136:151]
	v_exp_f32_e32 v100, v104
	v_exp_f32_e32 v101, v105
	v_exp_f32_e32 v102, v106
	v_exp_f32_e32 v103, v107
	s_waitcnt lgkmcnt(0)
	v_mfma_f32_32x32x16_bf16 v[120:135], v[92:95], v[168:171], v[120:135]
	v_exp_f32_e32 v104, v108
	v_exp_f32_e32 v105, v109
	v_exp_f32_e32 v106, v110
	v_exp_f32_e32 v107, v111
	s_cmp_gt_i32 s27, 2
	s_cselect_b32 s34, -3, 2
	s_add_i32 s34, s34, s27
	s_mulk_i32 s34, 0x2400
	v_add_u32_e32 v88, s29, v195
	s_min_u32 s29, s13, s12
	s_waitcnt vmcnt(3)
	ds_write_b128 v208, v[10:13] offset:18432
	v_add_u32_e32 v10, s34, v208
	s_lshl_b32 s92, s29, 13
	s_waitcnt vmcnt(2)
	ds_write_b128 v10, v[112:115] offset:36864
	ds_read_b128 v[240:243], v195 offset:9216
	ds_read_b128 v[244:247], v195 offset:13824
	ds_read_b128 v[10:13], v88 offset:41472
	ds_read_b128 v[64:67], v88 offset:36864
	ds_read_b128 v[68:71], v88 offset:36896
	ds_read_b128 v[72:75], v88 offset:41504
	ds_read_b128 v[76:79], v88 offset:36928
	ds_read_b128 v[80:83], v88 offset:41536
	ds_read_b128 v[84:87], v88 offset:36960
	ds_read_b128 v[88:91], v88 offset:41568
	s_add_u32 vcc_lo, s100, s92
	s_addc_u32 vcc_hi, s101, 0
	global_load_dwordx4 v[152:155], v248, vcc
	s_lshl_b32 s92, s28, 7
	s_add_u32 vcc_lo, s98, s92
	s_addc_u32 vcc_hi, s99, 0
	global_load_dwordx4 v[156:159], v249, vcc
	v_add_f32_e32 v1, v1, v187
	s_setprio 1
	v_mov_b32_e32 v109, v136
	v_cvt_pk_bf16_f32 v92, v14, v15
	v_cvt_pk_bf16_f32 v93, v116, v117
	v_cvt_pk_bf16_f32 v94, v118, v119
	v_cvt_pk_bf16_f32 v95, v184, v185
	s_waitcnt lgkmcnt(6)
	s_nop 0
	v_mfma_f32_32x32x16_bf16 v[16:31], v[64:67], v[92:95], v[16:31]
	v_max3_f32 v109, v109, v137, v138
	v_max3_f32 v109, v109, v139, v140
	v_add_f32_e32 v108, v14, v15
	v_add_f32_e32 v108, v108, v116
	v_add_f32_e32 v108, v108, v117
	s_nop 0
	v_mfma_f32_32x32x16_bf16 v[32:47], v[10:13], v[92:95], v[32:47]
	v_cvt_pk_bf16_f32 v64, v186, v210
	v_cvt_pk_bf16_f32 v65, v211, v212
	v_cvt_pk_bf16_f32 v66, v160, v161
	v_cvt_pk_bf16_f32 v67, v162, v163
	v_max3_f32 v109, v109, v141, v142
	v_max3_f32 v109, v109, v143, v144
	v_add_f32_e32 v108, v108, v118
	v_add_f32_e32 v108, v108, v119
	v_add_f32_e32 v108, v108, v184
	v_add_f32_e32 v108, v108, v185
	s_waitcnt lgkmcnt(5)
	v_mfma_f32_32x32x16_bf16 v[16:31], v[68:71], v[64:67], v[16:31]
	v_max3_f32 v109, v109, v145, v146
	v_max3_f32 v109, v109, v147, v148
	v_add_f32_e32 v108, v108, v186
	v_add_f32_e32 v108, v108, v210
	v_add_f32_e32 v108, v108, v211
	v_add_f32_e32 v108, v108, v212
	s_waitcnt lgkmcnt(4)
	v_mfma_f32_32x32x16_bf16 v[32:47], v[72:75], v[64:67], v[32:47]
	v_cvt_pk_bf16_f32 v10, v164, v165
	v_cvt_pk_bf16_f32 v11, v166, v167
	v_cvt_pk_bf16_f32 v12, v96, v97
	v_cvt_pk_bf16_f32 v13, v98, v99
	v_max3_f32 v109, v109, v149, v150
	v_max3_f32 v109, v109, v151, v120
	v_add_f32_e32 v108, v108, v160
	v_add_f32_e32 v108, v108, v161
	v_add_f32_e32 v108, v108, v162
	v_add_f32_e32 v108, v108, v163
	s_waitcnt lgkmcnt(3)
	v_mfma_f32_32x32x16_bf16 v[16:31], v[76:79], v[10:13], v[16:31]
	v_max3_f32 v109, v109, v121, v122
	v_max3_f32 v109, v109, v123, v124
	v_add_f32_e32 v108, v108, v164
	v_add_f32_e32 v108, v108, v165
	v_add_f32_e32 v108, v108, v166
	v_add_f32_e32 v108, v108, v167
	s_waitcnt lgkmcnt(2)
	v_mfma_f32_32x32x16_bf16 v[32:47], v[80:83], v[10:13], v[32:47]
	v_cvt_pk_bf16_f32 v64, v100, v101
	v_cvt_pk_bf16_f32 v65, v102, v103
	v_cvt_pk_bf16_f32 v66, v104, v105
	v_cvt_pk_bf16_f32 v67, v106, v107
	v_max3_f32 v109, v109, v125, v126
	v_max3_f32 v109, v109, v127, v128
	v_add_f32_e32 v108, v108, v96
	v_add_f32_e32 v108, v108, v97
	v_add_f32_e32 v108, v108, v98
	v_add_f32_e32 v108, v108, v99
	s_waitcnt lgkmcnt(1)
	v_mfma_f32_32x32x16_bf16 v[16:31], v[84:87], v[64:67], v[16:31]
	v_max3_f32 v109, v109, v129, v130
	v_max3_f32 v109, v109, v131, v132
	v_add_f32_e32 v108, v108, v100
	v_add_f32_e32 v108, v108, v101
	v_add_f32_e32 v108, v108, v102
	v_add_f32_e32 v108, v108, v103
	s_waitcnt lgkmcnt(0)
	v_mfma_f32_32x32x16_bf16 v[32:47], v[88:91], v[64:67], v[32:47]
	v_max3_f32 v109, v109, v133, v134
	v_max3_f32 v109, v109, v135, v135
	v_add_f32_e32 v108, v108, v104
	v_add_f32_e32 v108, v108, v105
	v_add_f32_e32 v108, v108, v106
	v_add_f32_e32 v108, v108, v107
	s_setprio 0
	ds_read_b128 v[164:167], v195 offset:9248
	ds_read_b128 v[160:163], v195 offset:13856
	ds_read_b128 v[74:77], v195 offset:9280
	ds_read_b128 v[66:69], v195 offset:9312
	ds_read_b128 v[70:73], v195 offset:13888
	ds_read_b128 v[10:13], v195 offset:13920
	v_add_f32_e32 v64, v1, v108
	v_mov_b32_e32 v1, v109
	s_nop 1
	v_permlane32_swap_b32_e32 v109, v1
	v_max_f32_e32 v1, v1, v1
	v_max_f32_e32 v14, v109, v109
	v_max_f32_e32 v1, v14, v1
	v_cmp_lt_f32_e32 vcc, s52, v1
	s_cbranch_vccz .LBB0_663
	v_max_f32_e32 v1, v1, v1
	v_max_f32_e32 v14, 0, v1
	v_add_f32_e32 v209, v209, v14
	v_xor_b32_e32 v48, 0x80000000, v209
	v_pk_add_f32 v[136:137], v[136:137], v[14:15] op_sel_hi:[1,0] neg_lo:[0,1] neg_hi:[0,1]
	v_pk_add_f32 v[120:121], v[120:121], v[14:15] op_sel_hi:[1,0] neg_lo:[0,1] neg_hi:[0,1]
	v_pk_add_f32 v[138:139], v[138:139], v[14:15] op_sel_hi:[1,0] neg_lo:[0,1] neg_hi:[0,1]
	v_pk_add_f32 v[122:123], v[122:123], v[14:15] op_sel_hi:[1,0] neg_lo:[0,1] neg_hi:[0,1]
	v_pk_add_f32 v[140:141], v[140:141], v[14:15] op_sel_hi:[1,0] neg_lo:[0,1] neg_hi:[0,1]
	v_pk_add_f32 v[124:125], v[124:125], v[14:15] op_sel_hi:[1,0] neg_lo:[0,1] neg_hi:[0,1]
	v_pk_add_f32 v[142:143], v[142:143], v[14:15] op_sel_hi:[1,0] neg_lo:[0,1] neg_hi:[0,1]
	v_pk_add_f32 v[126:127], v[126:127], v[14:15] op_sel_hi:[1,0] neg_lo:[0,1] neg_hi:[0,1]
	v_pk_add_f32 v[144:145], v[144:145], v[14:15] op_sel_hi:[1,0] neg_lo:[0,1] neg_hi:[0,1]
	v_pk_add_f32 v[128:129], v[128:129], v[14:15] op_sel_hi:[1,0] neg_lo:[0,1] neg_hi:[0,1]
	v_pk_add_f32 v[146:147], v[146:147], v[14:15] op_sel_hi:[1,0] neg_lo:[0,1] neg_hi:[0,1]
	v_pk_add_f32 v[130:131], v[130:131], v[14:15] op_sel_hi:[1,0] neg_lo:[0,1] neg_hi:[0,1]
	v_pk_add_f32 v[148:149], v[148:149], v[14:15] op_sel_hi:[1,0] neg_lo:[0,1] neg_hi:[0,1]
	v_pk_add_f32 v[132:133], v[132:133], v[14:15] op_sel_hi:[1,0] neg_lo:[0,1] neg_hi:[0,1]
	v_pk_add_f32 v[150:151], v[150:151], v[14:15] op_sel_hi:[1,0] neg_lo:[0,1] neg_hi:[0,1]
	v_pk_add_f32 v[134:135], v[134:135], v[14:15] op_sel_hi:[1,0] neg_lo:[0,1] neg_hi:[0,1]
	v_exp_f32_e64 v14, -v14
	v_mov_b32_e32 v49, v48
	v_mov_b32_e32 v50, v48
	v_mov_b32_e32 v51, v48
	v_mov_b32_e32 v52, v48
	v_mov_b32_e32 v53, v48
	v_mov_b32_e32 v54, v48
	v_mov_b32_e32 v55, v48
	v_mov_b32_e32 v56, v48
	v_mov_b32_e32 v57, v48
	v_mov_b32_e32 v58, v48
	v_mov_b32_e32 v59, v48
	v_mov_b32_e32 v60, v48
	v_mov_b32_e32 v61, v48
	v_mov_b32_e32 v62, v48
	v_mov_b32_e32 v63, v48
	s_nop 11
	v_pk_mul_f32 v[30:31], v[30:31], v[14:15] op_sel_hi:[1,0]
	v_pk_mul_f32 v[28:29], v[28:29], v[14:15] op_sel_hi:[1,0]
	v_pk_mul_f32 v[26:27], v[26:27], v[14:15] op_sel_hi:[1,0]
	v_pk_mul_f32 v[24:25], v[24:25], v[14:15] op_sel_hi:[1,0]
	v_pk_mul_f32 v[22:23], v[22:23], v[14:15] op_sel_hi:[1,0]
	v_pk_mul_f32 v[20:21], v[20:21], v[14:15] op_sel_hi:[1,0]
	v_pk_mul_f32 v[18:19], v[18:19], v[14:15] op_sel_hi:[1,0]
	v_pk_mul_f32 v[16:17], v[16:17], v[14:15] op_sel_hi:[1,0]
	v_pk_mul_f32 v[46:47], v[46:47], v[14:15] op_sel_hi:[1,0]
	v_pk_mul_f32 v[44:45], v[44:45], v[14:15] op_sel_hi:[1,0]
	v_pk_mul_f32 v[42:43], v[42:43], v[14:15] op_sel_hi:[1,0]
	v_pk_mul_f32 v[40:41], v[40:41], v[14:15] op_sel_hi:[1,0]
	v_pk_mul_f32 v[38:39], v[38:39], v[14:15] op_sel_hi:[1,0]
	v_pk_mul_f32 v[36:37], v[36:37], v[14:15] op_sel_hi:[1,0]
	v_pk_mul_f32 v[34:35], v[34:35], v[14:15] op_sel_hi:[1,0]
	v_pk_mul_f32 v[32:33], v[32:33], v[14:15] op_sel_hi:[1,0]
	v_mul_f32_e32 v64, v64, v14
